# GEMM K-loop phase-1 rebalanced: 2nd DMA moved to phase 2, B1 LDS reads + pointer SALU moved into MFMA gaps, B0 reads first via loop-invariant address VGPR
# baseline (speedup 1.0000x reference)
; #define PG8_STAGE(bufoff, gbase, voff) do { _Pragma("unroll") for (int _i = 0; _i < 2; ++_i) \
;         __builtin_amdgcn_global_load_lds((const unsigned*)((const char*)(gbase) + (voff)[_i]), (LAS unsigned*)(lds + (bufoff) + ldsw + _i * 8192), 16, 0, 0); } while (0)
; #define PG8_LDA(dst, b, h) do { _Pragma("unroll") for (int m = 0; m < 4; ++m) _Pragma("unroll") for (int k = 0; k < 2; ++k) dst[m][k] = *(const LAS bf16x8*)(lds + PG8_SA(b, h) + aoff + m * 2048 + k * 1024); } while (0)
; #define PG8_LDB(dst, b, h) do { _Pragma("unroll") for (int n = 0; n < 2; ++n) _Pragma("unroll") for (int k = 0; k < 2; ++k) dst[n][k] = *(const LAS bf16x8*)(lds + PG8_SB(b, h) + boff + n * 2048 + k * 1024); } while (0)
; #define PG8_MMA(ai, bj, At, Bt) do { __builtin_amdgcn_s_setprio(1); _Pragma("unroll") for (int m = 0; m < 4; ++m) _Pragma("unroll") for (int n = 0; n < 2; ++n) _Pragma("unroll") for (int k = 0; k < 2; ++k) \
;         acc[ai][bj][m][n] = __builtin_amdgcn_mfma_f32_16x16x32_bf16(Bt[n][k], At[m][k], acc[ai][bj][m][n], 0, 0, 0); __builtin_amdgcn_s_setprio(0); } while (0)
; #define PG8_WAIT_L(n) asm volatile("s_waitcnt lgkmcnt(" #n ")" ::: "memory")
; template <class Epi, class Sched>
; __device__ __forceinline__ void gemm_phase(LAS unsigned char* lds, const Gemm g, const Sched& S, const Epi& E, int tid) {
;     ...
;         const bool has_next = S.next(ui + 1, nxt);
;         const char* nA = has_next ? (const char*)g.A + (size_t)nxt.pm * tstep : cA; const char* nB = has_next ? (const char*)g.Bt + (size_t)nxt.pn * tstep : cB;
;         for (int t = 0; t < nt; t += 2) {
;             const bool last = (t == nt - 2);
;             const char* a1 = cA + (size_t)(t + 1) * kstep;
;             const char* a2 = last ? nA : cA + (size_t)(t + 2) * kstep; const char* b2 = last ? nB : cB + (size_t)(t + 2) * kstep;
;             const char* a3 = a2 + kstep; const char* b3 = b2 + kstep;
;             PG8_LDB(B0, 0, 0); PG8_SCHED; PG8_LDA(At, 0, 0); PG8_STAGE(PG8_SA(1, 1), a1 + hstep, voffA);
;             PG8_WAIT_L(8); PG8_BAR; PG8_WAIT_L(0); PG8_MMA(0, 0, At, B0); PG8_BAR; PG8_SCHED;
;             PG8_LDB(B1, 0, 1); PG8_STAGE(PG8_SB(0, 0), b2, voffB);
;             PG8_BAR; PG8_WAIT_L(0); PG8_MMA(0, 1, At, B1); PG8_BAR;
;             PG8_LDA(At, 0, 1); PG8_STAGE(PG8_SA(0, 0), a2, voffA);
;             PG8_BAR; PG8_WAIT_L(0); PG8_MMA(1, 0, At, B0); PG8_BAR; PG8_SCHED;
.LBB0_99:
	s_add_u32 vcc_lo, s44, 0x80
	s_addc_u32 vcc_hi, s45, 0
	s_add_u32 s96, s34, 0x100
	s_addc_u32 s65, s35, 0
	s_mov_b32 s34, 0
	v_add_u32_e32 v240, 0x10000, v141
	ds_read_b128 v[144:147], v240
	ds_read_b128 v[148:151], v240 offset:1024
	ds_read_b128 v[160:163], v240 offset:2048
	ds_read_b128 v[164:167], v240 offset:3072
	v_lshl_add_u64 v[152:153], vcc, 0, v[134:135]
	s_add_i32 m0, s88, 0xc000
	ds_read_b128 v[168:171], v143
	ds_read_b128 v[188:191], v143 offset:2048
	ds_read_b128 v[196:199], v143 offset:4096
	ds_read_b128 v[204:207], v143 offset:6144
	global_load_lds_dwordx4 v[152:153], off
	s_waitcnt lgkmcnt(4)
	s_setprio 1
	s_barrier
	s_waitcnt lgkmcnt(0)
	v_mfma_f32_16x16x32_bf16 v[124:127], v[144:147], v[168:171], 0
	ds_read_b128 v[184:187], v143 offset:1024
	s_add_i32 s0, s34, 2
	s_add_u32 s1, vcc_lo, 0x80
	v_mfma_f32_16x16x32_bf16 v[120:123], v[160:163], v[168:171], 0
	ds_read_b128 v[192:195], v143 offset:3072
	s_addc_u32 s35, vcc_hi, 0
	v_mfma_f32_16x16x32_bf16 v[116:119], v[144:147], v[188:191], 0
	ds_read_b128 v[200:203], v143 offset:5120
	s_add_i32 s17, 0, 0x10000
	v_mfma_f32_16x16x32_bf16 v[112:115], v[160:163], v[188:191], 0
	ds_read_b128 v[208:211], v143 offset:7168
	s_cmp_eq_u32 s95, s34
	v_mfma_f32_16x16x32_bf16 v[100:103], v[144:147], v[196:199], 0
	s_cselect_b32 s34, s38, s1
	v_mfma_f32_16x16x32_bf16 v[96:99], v[160:163], v[196:199], 0
	s_cselect_b32 s35, s39, s35
	v_mfma_f32_16x16x32_bf16 v[84:87], v[144:147], v[204:207], 0
	s_cselect_b32 s45, s41, s65
	v_mfma_f32_16x16x32_bf16 v[80:83], v[160:163], v[204:207], 0
	s_cselect_b32 s44, s40, s96
	s_waitcnt lgkmcnt(0)
	v_mfma_f32_16x16x32_bf16 v[124:127], v[148:151], v[184:187], v[124:127]
	s_add_i32 s1, 0, 0x14000
	v_add_u32_e32 v152, s1, v141
	v_mfma_f32_16x16x32_bf16 v[120:123], v[164:167], v[184:187], v[120:123]
	ds_read_b128 v[212:215], v152
	v_mfma_f32_16x16x32_bf16 v[116:119], v[148:151], v[192:195], v[116:119]
	ds_read_b128 v[216:219], v152 offset:1024
	v_mfma_f32_16x16x32_bf16 v[112:115], v[164:167], v[192:195], v[112:115]
	ds_read_b128 v[220:223], v152 offset:2048
	v_mfma_f32_16x16x32_bf16 v[100:103], v[148:151], v[200:203], v[100:103]
	ds_read_b128 v[224:227], v152 offset:3072
	v_mfma_f32_16x16x32_bf16 v[96:99], v[164:167], v[200:203], v[96:99]
	v_mfma_f32_16x16x32_bf16 v[84:87], v[148:151], v[208:211], v[84:87]
	v_mfma_f32_16x16x32_bf16 v[80:83], v[164:167], v[208:211], v[80:83]
	s_barrier
	s_setprio 0
	v_lshl_add_u64 v[238:239], vcc, 0, v[136:137]
	s_add_i32 m0, s88, 0xe000
	s_nop 0
	global_load_lds_dwordx4 v[238:239], off
	s_add_i32 s17, s17, s85
	v_lshl_add_u64 v[152:153], s[44:45], 0, v[154:155]
	s_mov_b32 m0, s17
	v_lshl_add_u64 v[228:229], s[44:45], 0, v[132:133]
	global_load_lds_dwordx4 v[152:153], off
	s_add_i32 m0, s17, 0x2000
	s_nop 0
	global_load_lds_dwordx4 v[228:229], off
	s_setprio 1
	s_barrier
	s_waitcnt lgkmcnt(0)
	v_mfma_f32_16x16x32_bf16 v[108:111], v[212:215], v[168:171], 0
	v_mfma_f32_16x16x32_bf16 v[104:107], v[220:223], v[168:171], 0
	v_mfma_f32_16x16x32_bf16 v[92:95], v[212:215], v[188:191], 0
	v_mfma_f32_16x16x32_bf16 v[88:91], v[220:223], v[188:191], 0
	v_mfma_f32_16x16x32_bf16 v[76:79], v[212:215], v[196:199], 0
	v_mfma_f32_16x16x32_bf16 v[72:75], v[220:223], v[196:199], 0
	s_mov_b32 m0, s88
	v_mfma_f32_16x16x32_bf16 v[68:71], v[212:215], v[204:207], 0
	v_lshl_add_u64 v[230:231], s[34:35], 0, v[128:129]
	v_mfma_f32_16x16x32_bf16 v[64:67], v[220:223], v[204:207], 0
	v_mfma_f32_16x16x32_bf16 v[108:111], v[216:219], v[184:187], v[108:111]
	v_mfma_f32_16x16x32_bf16 v[104:107], v[224:227], v[184:187], v[104:107]
	v_mfma_f32_16x16x32_bf16 v[92:95], v[216:219], v[192:195], v[92:95]
	v_mfma_f32_16x16x32_bf16 v[88:91], v[224:227], v[192:195], v[88:91]
	v_mfma_f32_16x16x32_bf16 v[76:79], v[216:219], v[200:203], v[76:79]
	v_mfma_f32_16x16x32_bf16 v[72:75], v[224:227], v[200:203], v[72:75]
	v_mfma_f32_16x16x32_bf16 v[68:71], v[216:219], v[208:211], v[68:71]
	v_mfma_f32_16x16x32_bf16 v[64:67], v[224:227], v[208:211], v[64:67]
	s_barrier
	s_setprio 0
	ds_read_b128 v[168:171], v143 offset:16384
	ds_read_b128 v[184:187], v143 offset:17408
	ds_read_b128 v[188:191], v143 offset:18432
	ds_read_b128 v[192:195], v143 offset:19456
	ds_read_b128 v[196:199], v143 offset:20480
	ds_read_b128 v[200:203], v143 offset:21504
	ds_read_b128 v[204:207], v143 offset:22528
	ds_read_b128 v[208:211], v143 offset:23552
	global_load_lds_dwordx4 v[230:231], off
	v_lshl_add_u64 v[232:233], s[34:35], 0, v[130:131]
	s_mov_b32 m0, s89
	s_nop 0
	global_load_lds_dwordx4 v[232:233], off
	s_setprio 1
	s_barrier
	s_waitcnt lgkmcnt(0)
	v_mfma_f32_16x16x32_bf16 v[60:63], v[144:147], v[168:171], 0
	v_mfma_f32_16x16x32_bf16 v[56:59], v[160:163], v[168:171], 0
	v_mfma_f32_16x16x32_bf16 v[52:55], v[144:147], v[188:191], 0
	v_mfma_f32_16x16x32_bf16 v[48:51], v[160:163], v[188:191], 0
	v_mfma_f32_16x16x32_bf16 v[36:39], v[144:147], v[196:199], 0
	v_mfma_f32_16x16x32_bf16 v[32:35], v[160:163], v[196:199], 0
	v_mfma_f32_16x16x32_bf16 v[20:23], v[144:147], v[204:207], 0
	v_mfma_f32_16x16x32_bf16 v[16:19], v[160:163], v[204:207], 0
	v_mfma_f32_16x16x32_bf16 v[60:63], v[148:151], v[184:187], v[60:63]
	v_mfma_f32_16x16x32_bf16 v[56:59], v[164:167], v[184:187], v[56:59]
	v_mfma_f32_16x16x32_bf16 v[52:55], v[148:151], v[192:195], v[52:55]
	v_mfma_f32_16x16x32_bf16 v[48:51], v[164:167], v[192:195], v[48:51]
	v_mfma_f32_16x16x32_bf16 v[36:39], v[148:151], v[200:203], v[36:39]
	v_mfma_f32_16x16x32_bf16 v[32:35], v[164:167], v[200:203], v[32:35]
	v_mfma_f32_16x16x32_bf16 v[20:23], v[148:151], v[208:211], v[20:23]
	v_mfma_f32_16x16x32_bf16 v[16:19], v[164:167], v[208:211], v[16:19]
	s_barrier
; #define PG8_STAGE(bufoff, gbase, voff) do { _Pragma("unroll") for (int _i = 0; _i < 2; ++_i) \
;         __builtin_amdgcn_global_load_lds((const unsigned*)((const char*)(gbase) + (voff)[_i]), (LAS unsigned*)(lds + (bufoff) + ldsw + _i * 8192), 16, 0, 0); } while (0)
; #define PG8_LDA(dst, b, h) do { _Pragma("unroll") for (int m = 0; m < 4; ++m) _Pragma("unroll") for (int k = 0; k < 2; ++k) dst[m][k] = *(const LAS bf16x8*)(lds + PG8_SA(b, h) + aoff + m * 2048 + k * 1024); } while (0)
; #define PG8_LDB(dst, b, h) do { _Pragma("unroll") for (int n = 0; n < 2; ++n) _Pragma("unroll") for (int k = 0; k < 2; ++k) dst[n][k] = *(const LAS bf16x8*)(lds + PG8_SB(b, h) + boff + n * 2048 + k * 1024); } while (0)
; #define PG8_MMA(ai, bj, At, Bt) do { __builtin_amdgcn_s_setprio(1); _Pragma("unroll") for (int m = 0; m < 4; ++m) _Pragma("unroll") for (int n = 0; n < 2; ++n) _Pragma("unroll") for (int k = 0; k < 2; ++k) \
;         acc[ai][bj][m][n] = __builtin_amdgcn_mfma_f32_16x16x32_bf16(Bt[n][k], At[m][k], acc[ai][bj][m][n], 0, 0, 0); __builtin_amdgcn_s_setprio(0); } while (0)
; #define PG8_WAIT_V(n) asm volatile("s_waitcnt vmcnt(" #n ")" ::: "memory")
; #define PG8_WAIT_L(n) asm volatile("s_waitcnt lgkmcnt(" #n ")" ::: "memory")
; #define PG8_BAR __builtin_amdgcn_s_barrier()
; #define PG8_SCHED __builtin_amdgcn_sched_barrier(0)
; template <class Epi, class Sched>
; __device__ __forceinline__ void gemm_phase(LAS unsigned char* lds, const Gemm g, const Sched& S, const Epi& E, int tid) {
;     ...
;             PG8_STAGE(PG8_SB(0, 1), b2 + hstep, voffB);
;             PG8_WAIT_V(6); PG8_BAR; PG8_MMA(1, 1, At, B1); PG8_BAR;
;             PG8_LDB(B0, 1, 0); PG8_SCHED; PG8_LDA(At, 1, 0); PG8_STAGE(PG8_SA(0, 1), a2 + hstep, voffA);
;             PG8_WAIT_L(8); PG8_BAR; PG8_WAIT_L(0); PG8_MMA(0, 0, At, B0); PG8_BAR; PG8_SCHED;
;             PG8_LDB(B1, 1, 1); PG8_STAGE(PG8_SB(1, 0), b3, voffB);
;             PG8_BAR; PG8_WAIT_L(0); PG8_MMA(0, 1, At, B1); PG8_BAR;
;             PG8_LDA(At, 1, 1); PG8_STAGE(PG8_SA(1, 0), a3, voffA);
	s_setprio 0
	s_add_u32 s44, s44, s6
	s_addc_u32 s45, s45, 0
	s_add_i32 s1, s1, s85
	v_lshl_add_u64 v[234:235], s[44:45], 0, v[154:155]
	s_mov_b32 m0, s1
	v_lshl_add_u64 v[236:237], s[44:45], 0, v[132:133]
	global_load_lds_dwordx4 v[234:235], off
	s_add_i32 m0, s1, 0x2000
	s_nop 0
	global_load_lds_dwordx4 v[236:237], off
	s_waitcnt vmcnt(24)
	s_setprio 1
	s_barrier
	v_mfma_f32_16x16x32_bf16 v[44:47], v[212:215], v[168:171], 0
	v_mfma_f32_16x16x32_bf16 v[40:43], v[220:223], v[168:171], 0
	v_mfma_f32_16x16x32_bf16 v[28:31], v[212:215], v[188:191], 0
	v_mfma_f32_16x16x32_bf16 v[24:27], v[220:223], v[188:191], 0
	v_mfma_f32_16x16x32_bf16 v[12:15], v[212:215], v[196:199], 0
	v_mfma_f32_16x16x32_bf16 v[8:11], v[220:223], v[196:199], 0
	s_add_i32 s1, 0, 0x18000
	v_mfma_f32_16x16x32_bf16 v[4:7], v[212:215], v[204:207], 0
	v_add_u32_e32 v164, s1, v141
	v_mfma_f32_16x16x32_bf16 v[0:3], v[220:223], v[204:207], 0
	v_mfma_f32_16x16x32_bf16 v[44:47], v[216:219], v[184:187], v[44:47]
	v_mfma_f32_16x16x32_bf16 v[40:43], v[224:227], v[184:187], v[40:43]
	v_mfma_f32_16x16x32_bf16 v[28:31], v[216:219], v[192:195], v[28:31]
	v_mfma_f32_16x16x32_bf16 v[24:27], v[224:227], v[192:195], v[24:27]
	v_mfma_f32_16x16x32_bf16 v[12:15], v[216:219], v[200:203], v[12:15]
	v_mfma_f32_16x16x32_bf16 v[8:11], v[224:227], v[200:203], v[8:11]
	v_mfma_f32_16x16x32_bf16 v[4:7], v[216:219], v[208:211], v[4:7]
	v_mfma_f32_16x16x32_bf16 v[0:3], v[224:227], v[208:211], v[0:3]
	s_barrier
	s_setprio 0
	ds_read_b128 v[144:147], v164
	ds_read_b128 v[148:151], v164 offset:1024
	ds_read_b128 v[160:163], v164 offset:2048
	ds_read_b128 v[164:167], v164 offset:3072
	s_add_u32 s34, s34, s6
	s_addc_u32 s35, s35, 0
	s_mov_b32 m0, s90
	v_lshl_add_u64 v[212:213], s[34:35], 0, v[128:129]
	ds_read_b128 v[168:171], v143 offset:32768
	ds_read_b128 v[188:191], v143 offset:34816
	ds_read_b128 v[196:199], v143 offset:36864
	ds_read_b128 v[204:207], v143 offset:38912
	global_load_lds_dwordx4 v[212:213], off
	s_waitcnt lgkmcnt(4)
	s_setprio 1
	s_barrier
	s_waitcnt lgkmcnt(0)
	v_mfma_f32_16x16x32_bf16 v[124:127], v[144:147], v[168:171], v[124:127]
	ds_read_b128 v[184:187], v143 offset:33792
	v_mfma_f32_16x16x32_bf16 v[120:123], v[160:163], v[168:171], v[120:123]
	ds_read_b128 v[192:195], v143 offset:35840
	v_mfma_f32_16x16x32_bf16 v[116:119], v[144:147], v[188:191], v[116:119]
	ds_read_b128 v[200:203], v143 offset:37888
	v_mfma_f32_16x16x32_bf16 v[112:115], v[160:163], v[188:191], v[112:115]
	ds_read_b128 v[208:211], v143 offset:39936
	v_mfma_f32_16x16x32_bf16 v[100:103], v[144:147], v[196:199], v[100:103]
	v_mfma_f32_16x16x32_bf16 v[96:99], v[160:163], v[196:199], v[96:99]
	v_mfma_f32_16x16x32_bf16 v[84:87], v[144:147], v[204:207], v[84:87]
	v_mfma_f32_16x16x32_bf16 v[80:83], v[160:163], v[204:207], v[80:83]
	s_waitcnt lgkmcnt(0)
	v_mfma_f32_16x16x32_bf16 v[124:127], v[148:151], v[184:187], v[124:127]
	s_add_i32 s17, 0, 0x1c000
	v_add_u32_e32 v183, s17, v141
	v_mfma_f32_16x16x32_bf16 v[120:123], v[164:167], v[184:187], v[120:123]
	ds_read_b128 v[212:215], v183
	v_mfma_f32_16x16x32_bf16 v[116:119], v[148:151], v[192:195], v[116:119]
	ds_read_b128 v[216:219], v183 offset:1024
	v_mfma_f32_16x16x32_bf16 v[112:115], v[164:167], v[192:195], v[112:115]
	ds_read_b128 v[220:223], v183 offset:2048
	v_mfma_f32_16x16x32_bf16 v[100:103], v[148:151], v[200:203], v[100:103]
	ds_read_b128 v[224:227], v183 offset:3072
	v_mfma_f32_16x16x32_bf16 v[96:99], v[164:167], v[200:203], v[96:99]
	v_mfma_f32_16x16x32_bf16 v[84:87], v[148:151], v[208:211], v[84:87]
	v_mfma_f32_16x16x32_bf16 v[80:83], v[164:167], v[208:211], v[80:83]
	s_barrier
	s_setprio 0
	v_lshl_add_u64 v[238:239], s[34:35], 0, v[130:131]
	s_mov_b32 m0, s91
	s_nop 0
	global_load_lds_dwordx4 v[238:239], off
	s_add_i32 s1, s1, s85
	v_lshl_add_u64 v[152:153], v[152:153], 0, s[8:9]
	s_mov_b32 m0, s1
	global_load_lds_dwordx4 v[152:153], off
	v_lshl_add_u64 v[152:153], v[228:229], 0, s[8:9]
	s_add_i32 m0, s1, 0x2000
	s_nop 0
	global_load_lds_dwordx4 v[152:153], off
	s_waitcnt vmcnt(10)
	s_setprio 1
	s_barrier
	s_waitcnt lgkmcnt(0)
	v_mfma_f32_16x16x32_bf16 v[108:111], v[212:215], v[168:171], v[108:111]
	v_mfma_f32_16x16x32_bf16 v[104:107], v[220:223], v[168:171], v[104:107]
	v_mfma_f32_16x16x32_bf16 v[92:95], v[212:215], v[188:191], v[92:95]
	v_mfma_f32_16x16x32_bf16 v[88:91], v[220:223], v[188:191], v[88:91]
	v_mfma_f32_16x16x32_bf16 v[76:79], v[212:215], v[196:199], v[76:79]
	v_mfma_f32_16x16x32_bf16 v[72:75], v[220:223], v[196:199], v[72:75]
	s_mov_b32 m0, s92
	v_mfma_f32_16x16x32_bf16 v[68:71], v[212:215], v[204:207], v[68:71]
	v_lshl_add_u64 v[152:153], v[230:231], 0, s[8:9]
	v_mfma_f32_16x16x32_bf16 v[64:67], v[220:223], v[204:207], v[64:67]
	v_mfma_f32_16x16x32_bf16 v[108:111], v[216:219], v[184:187], v[108:111]
	v_mfma_f32_16x16x32_bf16 v[104:107], v[224:227], v[184:187], v[104:107]
	v_mfma_f32_16x16x32_bf16 v[92:95], v[216:219], v[192:195], v[92:95]
	v_mfma_f32_16x16x32_bf16 v[88:91], v[224:227], v[192:195], v[88:91]
	v_mfma_f32_16x16x32_bf16 v[76:79], v[216:219], v[200:203], v[76:79]
	v_mfma_f32_16x16x32_bf16 v[72:75], v[224:227], v[200:203], v[72:75]
	v_mfma_f32_16x16x32_bf16 v[68:71], v[216:219], v[208:211], v[68:71]
	v_mfma_f32_16x16x32_bf16 v[64:67], v[224:227], v[208:211], v[64:67]
	s_barrier
	s_setprio 0
	ds_read_b128 v[168:171], v143 offset:49152
	ds_read_b128 v[184:187], v143 offset:50176
	ds_read_b128 v[188:191], v143 offset:51200
	ds_read_b128 v[192:195], v143 offset:52224
	ds_read_b128 v[196:199], v143 offset:53248
	ds_read_b128 v[200:203], v143 offset:54272
	ds_read_b128 v[204:207], v143 offset:55296
	ds_read_b128 v[208:211], v143 offset:56320
	global_load_lds_dwordx4 v[152:153], off
	v_lshl_add_u64 v[152:153], v[232:233], 0, s[8:9]
	s_mov_b32 m0, s93
	s_nop 0
	global_load_lds_dwordx4 v[152:153], off
	s_setprio 1
	s_barrier
; #define PG8_STAGE(bufoff, gbase, voff) do { _Pragma("unroll") for (int _i = 0; _i < 2; ++_i) \
;         __builtin_amdgcn_global_load_lds((const unsigned*)((const char*)(gbase) + (voff)[_i]), (LAS unsigned*)(lds + (bufoff) + ldsw + _i * 8192), 16, 0, 0); } while (0)
; #define PG8_LDA(dst, b, h) do { _Pragma("unroll") for (int m = 0; m < 4; ++m) _Pragma("unroll") for (int k = 0; k < 2; ++k) dst[m][k] = *(const LAS bf16x8*)(lds + PG8_SA(b, h) + aoff + m * 2048 + k * 1024); } while (0)
; #define PG8_LDB(dst, b, h) do { _Pragma("unroll") for (int n = 0; n < 2; ++n) _Pragma("unroll") for (int k = 0; k < 2; ++k) dst[n][k] = *(const LAS bf16x8*)(lds + PG8_SB(b, h) + boff + n * 2048 + k * 1024); } while (0)
; #define PG8_MMA(ai, bj, At, Bt) do { __builtin_amdgcn_s_setprio(1); _Pragma("unroll") for (int m = 0; m < 4; ++m) _Pragma("unroll") for (int n = 0; n < 2; ++n) _Pragma("unroll") for (int k = 0; k < 2; ++k) \
;         acc[ai][bj][m][n] = __builtin_amdgcn_mfma_f32_16x16x32_bf16(Bt[n][k], At[m][k], acc[ai][bj][m][n], 0, 0, 0); __builtin_amdgcn_s_setprio(0); } while (0)
; #define PG8_WAIT_V(n) asm volatile("s_waitcnt vmcnt(" #n ")" ::: "memory")
; #define PG8_WAIT_L(n) asm volatile("s_waitcnt lgkmcnt(" #n ")" ::: "memory")
; #define PG8_BAR __builtin_amdgcn_s_barrier()
; #define PG8_SCHED __builtin_amdgcn_sched_barrier(0)
; template <class Epi, class Sched>
; __device__ __forceinline__ void gemm_phase(LAS unsigned char* lds, const Gemm g, const Sched& S, const Epi& E, int tid) {
;     ...
;         for (int t = 0; t < nt; t += 2) {
;             const bool last = (t == nt - 2);
;             const char* a1 = cA + (size_t)(t + 1) * kstep;
;             const char* a2 = last ? nA : cA + (size_t)(t + 2) * kstep; const char* b2 = last ? nB : cB + (size_t)(t + 2) * kstep;
;             const char* a3 = a2 + kstep; const char* b3 = b2 + kstep;
;             PG8_LDB(B0, 0, 0); PG8_SCHED; PG8_LDA(At, 0, 0); PG8_STAGE(PG8_SA(1, 1), a1 + hstep, voffA);
;             PG8_WAIT_L(8); PG8_BAR; PG8_WAIT_L(0); PG8_MMA(0, 0, At, B0); PG8_BAR; PG8_SCHED;
;             PG8_LDB(B1, 0, 1); PG8_STAGE(PG8_SB(0, 0), b2, voffB);
;     ...
;             PG8_BAR; PG8_WAIT_L(0); PG8_MMA(1, 0, At, B0); PG8_BAR; PG8_SCHED;
;             PG8_STAGE(PG8_SB(1, 1), b3 + hstep, voffB);
;             PG8_WAIT_V(6); PG8_BAR; PG8_MMA(1, 1, At, B1); PG8_BAR;
	s_waitcnt lgkmcnt(0)
	v_mfma_f32_16x16x32_bf16 v[60:63], v[144:147], v[168:171], v[60:63]
	v_mfma_f32_16x16x32_bf16 v[56:59], v[160:163], v[168:171], v[56:59]
	v_mfma_f32_16x16x32_bf16 v[52:55], v[144:147], v[188:191], v[52:55]
	v_mfma_f32_16x16x32_bf16 v[48:51], v[160:163], v[188:191], v[48:51]
	v_mfma_f32_16x16x32_bf16 v[36:39], v[144:147], v[196:199], v[36:39]
	v_mfma_f32_16x16x32_bf16 v[32:35], v[160:163], v[196:199], v[32:35]
	v_mfma_f32_16x16x32_bf16 v[20:23], v[144:147], v[204:207], v[20:23]
	v_mfma_f32_16x16x32_bf16 v[16:19], v[160:163], v[204:207], v[16:19]
	v_mfma_f32_16x16x32_bf16 v[60:63], v[148:151], v[184:187], v[60:63]
	v_mfma_f32_16x16x32_bf16 v[56:59], v[164:167], v[184:187], v[56:59]
	v_mfma_f32_16x16x32_bf16 v[52:55], v[148:151], v[192:195], v[52:55]
	v_mfma_f32_16x16x32_bf16 v[48:51], v[164:167], v[192:195], v[48:51]
	v_mfma_f32_16x16x32_bf16 v[36:39], v[148:151], v[200:203], v[36:39]
	v_mfma_f32_16x16x32_bf16 v[32:35], v[164:167], v[200:203], v[32:35]
	v_mfma_f32_16x16x32_bf16 v[20:23], v[148:151], v[208:211], v[20:23]
	v_mfma_f32_16x16x32_bf16 v[16:19], v[164:167], v[208:211], v[16:19]
	s_barrier
	s_setprio 0
	s_add_i32 s1, s17, s85
	v_lshl_add_u64 v[144:145], v[234:235], 0, s[8:9]
	s_mov_b32 m0, s1
	s_nop 0
	global_load_lds_dwordx4 v[144:145], off
	v_lshl_add_u64 v[144:145], v[236:237], 0, s[8:9]
	s_add_i32 m0, s1, 0x2000
	s_nop 0
	global_load_lds_dwordx4 v[144:145], off
	s_waitcnt vmcnt(6)
	s_setprio 1
	s_barrier
	v_mfma_f32_16x16x32_bf16 v[44:47], v[212:215], v[168:171], v[44:47]
	v_mfma_f32_16x16x32_bf16 v[40:43], v[220:223], v[168:171], v[40:43]
	v_mfma_f32_16x16x32_bf16 v[28:31], v[212:215], v[188:191], v[28:31]
	v_mfma_f32_16x16x32_bf16 v[24:27], v[220:223], v[188:191], v[24:27]
	v_mfma_f32_16x16x32_bf16 v[12:15], v[212:215], v[196:199], v[12:15]
	v_mfma_f32_16x16x32_bf16 v[8:11], v[220:223], v[196:199], v[8:11]
	s_add_u32 vcc_lo, vcc_lo, 0x100
	v_mfma_f32_16x16x32_bf16 v[4:7], v[212:215], v[204:207], v[4:7]
	s_addc_u32 vcc_hi, vcc_hi, 0
	v_mfma_f32_16x16x32_bf16 v[0:3], v[220:223], v[204:207], v[0:3]
	s_add_u32 s96, s96, 0x100
	v_mfma_f32_16x16x32_bf16 v[44:47], v[216:219], v[184:187], v[44:47]
	s_addc_u32 s65, s65, 0
	v_mfma_f32_16x16x32_bf16 v[40:43], v[224:227], v[184:187], v[40:43]
	s_cmp_ge_u32 s0, s94
	v_mfma_f32_16x16x32_bf16 v[28:31], v[216:219], v[192:195], v[28:31]
	s_mov_b32 s34, s0
	v_mfma_f32_16x16x32_bf16 v[24:27], v[224:227], v[192:195], v[24:27]
	v_mfma_f32_16x16x32_bf16 v[12:15], v[216:219], v[200:203], v[12:15]
	v_mfma_f32_16x16x32_bf16 v[8:11], v[224:227], v[200:203], v[8:11]
	v_mfma_f32_16x16x32_bf16 v[4:7], v[216:219], v[208:211], v[4:7]
	v_mfma_f32_16x16x32_bf16 v[0:3], v[224:227], v[208:211], v[0:3]
	s_barrier
	s_setprio 0
	s_cbranch_scc1 .Lpeel_exit_plain
.LBB0_100:
	ds_read_b128 v[144:147], v240
	ds_read_b128 v[148:151], v240 offset:1024
	ds_read_b128 v[160:163], v240 offset:2048
	ds_read_b128 v[164:167], v240 offset:3072
	v_lshl_add_u64 v[152:153], vcc, 0, v[134:135]
	s_add_i32 m0, s88, 0xc000
	ds_read_b128 v[168:171], v143
	ds_read_b128 v[188:191], v143 offset:2048
	ds_read_b128 v[196:199], v143 offset:4096
	ds_read_b128 v[204:207], v143 offset:6144
	global_load_lds_dwordx4 v[152:153], off
	s_waitcnt lgkmcnt(4)
	s_setprio 1
	s_barrier
	s_waitcnt lgkmcnt(0)
	v_mfma_f32_16x16x32_bf16 v[124:127], v[144:147], v[168:171], v[124:127]
	ds_read_b128 v[184:187], v143 offset:1024
	s_add_i32 s0, s34, 2
	s_add_u32 s1, vcc_lo, 0x80
	v_mfma_f32_16x16x32_bf16 v[120:123], v[160:163], v[168:171], v[120:123]
	ds_read_b128 v[192:195], v143 offset:3072
	s_addc_u32 s35, vcc_hi, 0
	v_mfma_f32_16x16x32_bf16 v[116:119], v[144:147], v[188:191], v[116:119]
	ds_read_b128 v[200:203], v143 offset:5120
	s_add_i32 s17, 0, 0x10000
	v_mfma_f32_16x16x32_bf16 v[112:115], v[160:163], v[188:191], v[112:115]
	ds_read_b128 v[208:211], v143 offset:7168
	s_cmp_eq_u32 s95, s34
	v_mfma_f32_16x16x32_bf16 v[100:103], v[144:147], v[196:199], v[100:103]
	s_cselect_b32 s34, s38, s1
	v_mfma_f32_16x16x32_bf16 v[96:99], v[160:163], v[196:199], v[96:99]
	s_cselect_b32 s35, s39, s35
	v_mfma_f32_16x16x32_bf16 v[84:87], v[144:147], v[204:207], v[84:87]
	s_cselect_b32 s45, s41, s65
	v_mfma_f32_16x16x32_bf16 v[80:83], v[160:163], v[204:207], v[80:83]
	s_cselect_b32 s44, s40, s96
	s_waitcnt lgkmcnt(0)
	v_mfma_f32_16x16x32_bf16 v[124:127], v[148:151], v[184:187], v[124:127]
	s_add_i32 s1, 0, 0x14000
	v_add_u32_e32 v152, s1, v141
	v_mfma_f32_16x16x32_bf16 v[120:123], v[164:167], v[184:187], v[120:123]
	ds_read_b128 v[212:215], v152
	v_mfma_f32_16x16x32_bf16 v[116:119], v[148:151], v[192:195], v[116:119]
	ds_read_b128 v[216:219], v152 offset:1024
	v_mfma_f32_16x16x32_bf16 v[112:115], v[164:167], v[192:195], v[112:115]
	ds_read_b128 v[220:223], v152 offset:2048
	v_mfma_f32_16x16x32_bf16 v[100:103], v[148:151], v[200:203], v[100:103]
	ds_read_b128 v[224:227], v152 offset:3072
	v_mfma_f32_16x16x32_bf16 v[96:99], v[164:167], v[200:203], v[96:99]
	v_mfma_f32_16x16x32_bf16 v[84:87], v[148:151], v[208:211], v[84:87]
	v_mfma_f32_16x16x32_bf16 v[80:83], v[164:167], v[208:211], v[80:83]
	s_barrier
	s_setprio 0
	v_lshl_add_u64 v[238:239], vcc, 0, v[136:137]
	s_add_i32 m0, s88, 0xe000
	s_nop 0
	global_load_lds_dwordx4 v[238:239], off
	s_add_i32 s17, s17, s85
	v_lshl_add_u64 v[152:153], s[44:45], 0, v[154:155]
	s_mov_b32 m0, s17
	v_lshl_add_u64 v[228:229], s[44:45], 0, v[132:133]
	global_load_lds_dwordx4 v[152:153], off
	s_add_i32 m0, s17, 0x2000
	s_nop 0
	global_load_lds_dwordx4 v[228:229], off
	s_setprio 1
	s_barrier
; #define PG8_STAGE(bufoff, gbase, voff) do { _Pragma("unroll") for (int _i = 0; _i < 2; ++_i) \
;         __builtin_amdgcn_global_load_lds((const unsigned*)((const char*)(gbase) + (voff)[_i]), (LAS unsigned*)(lds + (bufoff) + ldsw + _i * 8192), 16, 0, 0); } while (0)
; #define PG8_LDA(dst, b, h) do { _Pragma("unroll") for (int m = 0; m < 4; ++m) _Pragma("unroll") for (int k = 0; k < 2; ++k) dst[m][k] = *(const LAS bf16x8*)(lds + PG8_SA(b, h) + aoff + m * 2048 + k * 1024); } while (0)
; #define PG8_LDB(dst, b, h) do { _Pragma("unroll") for (int n = 0; n < 2; ++n) _Pragma("unroll") for (int k = 0; k < 2; ++k) dst[n][k] = *(const LAS bf16x8*)(lds + PG8_SB(b, h) + boff + n * 2048 + k * 1024); } while (0)
; #define PG8_MMA(ai, bj, At, Bt) do { __builtin_amdgcn_s_setprio(1); _Pragma("unroll") for (int m = 0; m < 4; ++m) _Pragma("unroll") for (int n = 0; n < 2; ++n) _Pragma("unroll") for (int k = 0; k < 2; ++k) \
;         acc[ai][bj][m][n] = __builtin_amdgcn_mfma_f32_16x16x32_bf16(Bt[n][k], At[m][k], acc[ai][bj][m][n], 0, 0, 0); __builtin_amdgcn_s_setprio(0); } while (0)
; #define PG8_WAIT_V(n) asm volatile("s_waitcnt vmcnt(" #n ")" ::: "memory")
; #define PG8_WAIT_L(n) asm volatile("s_waitcnt lgkmcnt(" #n ")" ::: "memory")
; #define PG8_BAR __builtin_amdgcn_s_barrier()
; #define PG8_SCHED __builtin_amdgcn_sched_barrier(0)
; template <class Epi, class Sched>
; __device__ __forceinline__ void gemm_phase(LAS unsigned char* lds, const Gemm g, const Sched& S, const Epi& E, int tid) {
;     ...
;             PG8_BAR; PG8_WAIT_L(0); PG8_MMA(0, 1, At, B1); PG8_BAR;
;             PG8_LDA(At, 0, 1); PG8_STAGE(PG8_SA(0, 0), a2, voffA);
;             PG8_BAR; PG8_WAIT_L(0); PG8_MMA(1, 0, At, B0); PG8_BAR; PG8_SCHED;
;             PG8_STAGE(PG8_SB(0, 1), b2 + hstep, voffB);
;             PG8_WAIT_V(6); PG8_BAR; PG8_MMA(1, 1, At, B1); PG8_BAR;
;             PG8_LDB(B0, 1, 0); PG8_SCHED; PG8_LDA(At, 1, 0); PG8_STAGE(PG8_SA(0, 1), a2 + hstep, voffA);
	s_waitcnt lgkmcnt(0)
	v_mfma_f32_16x16x32_bf16 v[108:111], v[212:215], v[168:171], v[108:111]
	v_mfma_f32_16x16x32_bf16 v[104:107], v[220:223], v[168:171], v[104:107]
	v_mfma_f32_16x16x32_bf16 v[92:95], v[212:215], v[188:191], v[92:95]
	v_mfma_f32_16x16x32_bf16 v[88:91], v[220:223], v[188:191], v[88:91]
	v_mfma_f32_16x16x32_bf16 v[76:79], v[212:215], v[196:199], v[76:79]
	v_mfma_f32_16x16x32_bf16 v[72:75], v[220:223], v[196:199], v[72:75]
	s_mov_b32 m0, s88
	v_mfma_f32_16x16x32_bf16 v[68:71], v[212:215], v[204:207], v[68:71]
	v_lshl_add_u64 v[230:231], s[34:35], 0, v[128:129]
	v_mfma_f32_16x16x32_bf16 v[64:67], v[220:223], v[204:207], v[64:67]
	v_mfma_f32_16x16x32_bf16 v[108:111], v[216:219], v[184:187], v[108:111]
	v_mfma_f32_16x16x32_bf16 v[104:107], v[224:227], v[184:187], v[104:107]
	v_mfma_f32_16x16x32_bf16 v[92:95], v[216:219], v[192:195], v[92:95]
	v_mfma_f32_16x16x32_bf16 v[88:91], v[224:227], v[192:195], v[88:91]
	v_mfma_f32_16x16x32_bf16 v[76:79], v[216:219], v[200:203], v[76:79]
	v_mfma_f32_16x16x32_bf16 v[72:75], v[224:227], v[200:203], v[72:75]
	v_mfma_f32_16x16x32_bf16 v[68:71], v[216:219], v[208:211], v[68:71]
	v_mfma_f32_16x16x32_bf16 v[64:67], v[224:227], v[208:211], v[64:67]
	s_barrier
	s_setprio 0
	ds_read_b128 v[168:171], v143 offset:16384
	ds_read_b128 v[184:187], v143 offset:17408
	ds_read_b128 v[188:191], v143 offset:18432
	ds_read_b128 v[192:195], v143 offset:19456
	ds_read_b128 v[196:199], v143 offset:20480
	ds_read_b128 v[200:203], v143 offset:21504
	ds_read_b128 v[204:207], v143 offset:22528
	ds_read_b128 v[208:211], v143 offset:23552
	global_load_lds_dwordx4 v[230:231], off
	v_lshl_add_u64 v[232:233], s[34:35], 0, v[130:131]
	s_mov_b32 m0, s89
	s_nop 0
	global_load_lds_dwordx4 v[232:233], off
	s_setprio 1
	s_barrier
	s_waitcnt lgkmcnt(0)
	v_mfma_f32_16x16x32_bf16 v[60:63], v[144:147], v[168:171], v[60:63]
	v_mfma_f32_16x16x32_bf16 v[56:59], v[160:163], v[168:171], v[56:59]
	v_mfma_f32_16x16x32_bf16 v[52:55], v[144:147], v[188:191], v[52:55]
	v_mfma_f32_16x16x32_bf16 v[48:51], v[160:163], v[188:191], v[48:51]
	v_mfma_f32_16x16x32_bf16 v[36:39], v[144:147], v[196:199], v[36:39]
	v_mfma_f32_16x16x32_bf16 v[32:35], v[160:163], v[196:199], v[32:35]
	v_mfma_f32_16x16x32_bf16 v[20:23], v[144:147], v[204:207], v[20:23]
	v_mfma_f32_16x16x32_bf16 v[16:19], v[160:163], v[204:207], v[16:19]
	v_mfma_f32_16x16x32_bf16 v[60:63], v[148:151], v[184:187], v[60:63]
	v_mfma_f32_16x16x32_bf16 v[56:59], v[164:167], v[184:187], v[56:59]
	v_mfma_f32_16x16x32_bf16 v[52:55], v[148:151], v[192:195], v[52:55]
	v_mfma_f32_16x16x32_bf16 v[48:51], v[164:167], v[192:195], v[48:51]
	v_mfma_f32_16x16x32_bf16 v[36:39], v[148:151], v[200:203], v[36:39]
	v_mfma_f32_16x16x32_bf16 v[32:35], v[164:167], v[200:203], v[32:35]
	v_mfma_f32_16x16x32_bf16 v[20:23], v[148:151], v[208:211], v[20:23]
	v_mfma_f32_16x16x32_bf16 v[16:19], v[164:167], v[208:211], v[16:19]
	s_barrier
	s_setprio 0
	s_add_u32 s44, s44, s6
	s_addc_u32 s45, s45, 0
	s_add_i32 s1, s1, s85
	v_lshl_add_u64 v[234:235], s[44:45], 0, v[154:155]
	s_mov_b32 m0, s1
	v_lshl_add_u64 v[236:237], s[44:45], 0, v[132:133]
	global_load_lds_dwordx4 v[234:235], off
	s_add_i32 m0, s1, 0x2000
	s_nop 0
	global_load_lds_dwordx4 v[236:237], off
	s_waitcnt vmcnt(6)
	s_setprio 1
	s_barrier
	v_mfma_f32_16x16x32_bf16 v[44:47], v[212:215], v[168:171], v[44:47]
	v_mfma_f32_16x16x32_bf16 v[40:43], v[220:223], v[168:171], v[40:43]
	v_mfma_f32_16x16x32_bf16 v[28:31], v[212:215], v[188:191], v[28:31]
	v_mfma_f32_16x16x32_bf16 v[24:27], v[220:223], v[188:191], v[24:27]
	v_mfma_f32_16x16x32_bf16 v[12:15], v[212:215], v[196:199], v[12:15]
	v_mfma_f32_16x16x32_bf16 v[8:11], v[220:223], v[196:199], v[8:11]
	s_add_i32 s1, 0, 0x18000
	v_mfma_f32_16x16x32_bf16 v[4:7], v[212:215], v[204:207], v[4:7]
	v_add_u32_e32 v164, s1, v141
	v_mfma_f32_16x16x32_bf16 v[0:3], v[220:223], v[204:207], v[0:3]
	v_mfma_f32_16x16x32_bf16 v[44:47], v[216:219], v[184:187], v[44:47]
	v_mfma_f32_16x16x32_bf16 v[40:43], v[224:227], v[184:187], v[40:43]
	v_mfma_f32_16x16x32_bf16 v[28:31], v[216:219], v[192:195], v[28:31]
	v_mfma_f32_16x16x32_bf16 v[24:27], v[224:227], v[192:195], v[24:27]
	v_mfma_f32_16x16x32_bf16 v[12:15], v[216:219], v[200:203], v[12:15]
	v_mfma_f32_16x16x32_bf16 v[8:11], v[224:227], v[200:203], v[8:11]
	v_mfma_f32_16x16x32_bf16 v[4:7], v[216:219], v[208:211], v[4:7]
	v_mfma_f32_16x16x32_bf16 v[0:3], v[224:227], v[208:211], v[0:3]
	s_barrier
	s_setprio 0
	ds_read_b128 v[144:147], v164
	ds_read_b128 v[148:151], v164 offset:1024
	ds_read_b128 v[160:163], v164 offset:2048
	ds_read_b128 v[164:167], v164 offset:3072
	s_add_u32 s34, s34, s6
	s_addc_u32 s35, s35, 0
	s_mov_b32 m0, s90
	v_lshl_add_u64 v[212:213], s[34:35], 0, v[128:129]
	ds_read_b128 v[168:171], v143 offset:32768
	ds_read_b128 v[188:191], v143 offset:34816
	ds_read_b128 v[196:199], v143 offset:36864
	ds_read_b128 v[204:207], v143 offset:38912
	global_load_lds_dwordx4 v[212:213], off
	s_waitcnt lgkmcnt(4)
	s_setprio 1
	s_barrier
; #define PG8_STAGE(bufoff, gbase, voff) do { _Pragma("unroll") for (int _i = 0; _i < 2; ++_i) \
;         __builtin_amdgcn_global_load_lds((const unsigned*)((const char*)(gbase) + (voff)[_i]), (LAS unsigned*)(lds + (bufoff) + ldsw + _i * 8192), 16, 0, 0); } while (0)
; #define PG8_LDA(dst, b, h) do { _Pragma("unroll") for (int m = 0; m < 4; ++m) _Pragma("unroll") for (int k = 0; k < 2; ++k) dst[m][k] = *(const LAS bf16x8*)(lds + PG8_SA(b, h) + aoff + m * 2048 + k * 1024); } while (0)
; #define PG8_LDB(dst, b, h) do { _Pragma("unroll") for (int n = 0; n < 2; ++n) _Pragma("unroll") for (int k = 0; k < 2; ++k) dst[n][k] = *(const LAS bf16x8*)(lds + PG8_SB(b, h) + boff + n * 2048 + k * 1024); } while (0)
; #define PG8_MMA(ai, bj, At, Bt) do { __builtin_amdgcn_s_setprio(1); _Pragma("unroll") for (int m = 0; m < 4; ++m) _Pragma("unroll") for (int n = 0; n < 2; ++n) _Pragma("unroll") for (int k = 0; k < 2; ++k) \
;         acc[ai][bj][m][n] = __builtin_amdgcn_mfma_f32_16x16x32_bf16(Bt[n][k], At[m][k], acc[ai][bj][m][n], 0, 0, 0); __builtin_amdgcn_s_setprio(0); } while (0)
; #define PG8_WAIT_V(n) asm volatile("s_waitcnt vmcnt(" #n ")" ::: "memory")
; #define PG8_WAIT_L(n) asm volatile("s_waitcnt lgkmcnt(" #n ")" ::: "memory")
; #define PG8_BAR __builtin_amdgcn_s_barrier()
; #define PG8_SCHED __builtin_amdgcn_sched_barrier(0)
; template <class Epi, class Sched>
; __device__ __forceinline__ void gemm_phase(LAS unsigned char* lds, const Gemm g, const Sched& S, const Epi& E, int tid) {
;     ...
;             PG8_WAIT_L(8); PG8_BAR; PG8_WAIT_L(0); PG8_MMA(0, 0, At, B0); PG8_BAR; PG8_SCHED;
;             PG8_LDB(B1, 1, 1); PG8_STAGE(PG8_SB(1, 0), b3, voffB);
;             PG8_BAR; PG8_WAIT_L(0); PG8_MMA(0, 1, At, B1); PG8_BAR;
;             PG8_LDA(At, 1, 1); PG8_STAGE(PG8_SA(1, 0), a3, voffA);
;             PG8_BAR; PG8_WAIT_L(0); PG8_MMA(1, 0, At, B0); PG8_BAR; PG8_SCHED;
;             PG8_STAGE(PG8_SB(1, 1), b3 + hstep, voffB);
;             PG8_WAIT_V(6); PG8_BAR; PG8_MMA(1, 1, At, B1); PG8_BAR;
	s_waitcnt lgkmcnt(0)
	v_mfma_f32_16x16x32_bf16 v[124:127], v[144:147], v[168:171], v[124:127]
	ds_read_b128 v[184:187], v143 offset:33792
	v_mfma_f32_16x16x32_bf16 v[120:123], v[160:163], v[168:171], v[120:123]
	ds_read_b128 v[192:195], v143 offset:35840
	v_mfma_f32_16x16x32_bf16 v[116:119], v[144:147], v[188:191], v[116:119]
	ds_read_b128 v[200:203], v143 offset:37888
	v_mfma_f32_16x16x32_bf16 v[112:115], v[160:163], v[188:191], v[112:115]
	ds_read_b128 v[208:211], v143 offset:39936
	v_mfma_f32_16x16x32_bf16 v[100:103], v[144:147], v[196:199], v[100:103]
	v_mfma_f32_16x16x32_bf16 v[96:99], v[160:163], v[196:199], v[96:99]
	v_mfma_f32_16x16x32_bf16 v[84:87], v[144:147], v[204:207], v[84:87]
	v_mfma_f32_16x16x32_bf16 v[80:83], v[160:163], v[204:207], v[80:83]
	s_waitcnt lgkmcnt(0)
	v_mfma_f32_16x16x32_bf16 v[124:127], v[148:151], v[184:187], v[124:127]
	s_add_i32 s17, 0, 0x1c000
	v_add_u32_e32 v183, s17, v141
	v_mfma_f32_16x16x32_bf16 v[120:123], v[164:167], v[184:187], v[120:123]
	ds_read_b128 v[212:215], v183
	v_mfma_f32_16x16x32_bf16 v[116:119], v[148:151], v[192:195], v[116:119]
	ds_read_b128 v[216:219], v183 offset:1024
	v_mfma_f32_16x16x32_bf16 v[112:115], v[164:167], v[192:195], v[112:115]
	ds_read_b128 v[220:223], v183 offset:2048
	v_mfma_f32_16x16x32_bf16 v[100:103], v[148:151], v[200:203], v[100:103]
	ds_read_b128 v[224:227], v183 offset:3072
	v_mfma_f32_16x16x32_bf16 v[96:99], v[164:167], v[200:203], v[96:99]
	v_mfma_f32_16x16x32_bf16 v[84:87], v[148:151], v[208:211], v[84:87]
	v_mfma_f32_16x16x32_bf16 v[80:83], v[164:167], v[208:211], v[80:83]
	s_barrier
	s_setprio 0
	v_lshl_add_u64 v[238:239], s[34:35], 0, v[130:131]
	s_mov_b32 m0, s91
	s_nop 0
	global_load_lds_dwordx4 v[238:239], off
	s_add_i32 s1, s1, s85
	v_lshl_add_u64 v[152:153], v[152:153], 0, s[8:9]
	s_mov_b32 m0, s1
	global_load_lds_dwordx4 v[152:153], off
	v_lshl_add_u64 v[152:153], v[228:229], 0, s[8:9]
	s_add_i32 m0, s1, 0x2000
	s_nop 0
	global_load_lds_dwordx4 v[152:153], off
	s_setprio 1
	s_barrier
	s_waitcnt lgkmcnt(0)
	v_mfma_f32_16x16x32_bf16 v[108:111], v[212:215], v[168:171], v[108:111]
	v_mfma_f32_16x16x32_bf16 v[104:107], v[220:223], v[168:171], v[104:107]
	v_mfma_f32_16x16x32_bf16 v[92:95], v[212:215], v[188:191], v[92:95]
	v_mfma_f32_16x16x32_bf16 v[88:91], v[220:223], v[188:191], v[88:91]
	v_mfma_f32_16x16x32_bf16 v[76:79], v[212:215], v[196:199], v[76:79]
	v_mfma_f32_16x16x32_bf16 v[72:75], v[220:223], v[196:199], v[72:75]
	s_mov_b32 m0, s92
	v_mfma_f32_16x16x32_bf16 v[68:71], v[212:215], v[204:207], v[68:71]
	v_lshl_add_u64 v[152:153], v[230:231], 0, s[8:9]
	v_mfma_f32_16x16x32_bf16 v[64:67], v[220:223], v[204:207], v[64:67]
	v_mfma_f32_16x16x32_bf16 v[108:111], v[216:219], v[184:187], v[108:111]
	v_mfma_f32_16x16x32_bf16 v[104:107], v[224:227], v[184:187], v[104:107]
	v_mfma_f32_16x16x32_bf16 v[92:95], v[216:219], v[192:195], v[92:95]
	v_mfma_f32_16x16x32_bf16 v[88:91], v[224:227], v[192:195], v[88:91]
	v_mfma_f32_16x16x32_bf16 v[76:79], v[216:219], v[200:203], v[76:79]
	v_mfma_f32_16x16x32_bf16 v[72:75], v[224:227], v[200:203], v[72:75]
	v_mfma_f32_16x16x32_bf16 v[68:71], v[216:219], v[208:211], v[68:71]
	v_mfma_f32_16x16x32_bf16 v[64:67], v[224:227], v[208:211], v[64:67]
	s_barrier
	s_setprio 0
	ds_read_b128 v[168:171], v143 offset:49152
	ds_read_b128 v[184:187], v143 offset:50176
	ds_read_b128 v[188:191], v143 offset:51200
	ds_read_b128 v[192:195], v143 offset:52224
	ds_read_b128 v[196:199], v143 offset:53248
	ds_read_b128 v[200:203], v143 offset:54272
	ds_read_b128 v[204:207], v143 offset:55296
	ds_read_b128 v[208:211], v143 offset:56320
	global_load_lds_dwordx4 v[152:153], off
	v_lshl_add_u64 v[152:153], v[232:233], 0, s[8:9]
	s_mov_b32 m0, s93
	s_nop 0
	global_load_lds_dwordx4 v[152:153], off
	s_setprio 1
	s_barrier
	s_waitcnt lgkmcnt(0)
	v_mfma_f32_16x16x32_bf16 v[60:63], v[144:147], v[168:171], v[60:63]
	v_mfma_f32_16x16x32_bf16 v[56:59], v[160:163], v[168:171], v[56:59]
	v_mfma_f32_16x16x32_bf16 v[52:55], v[144:147], v[188:191], v[52:55]
	v_mfma_f32_16x16x32_bf16 v[48:51], v[160:163], v[188:191], v[48:51]
	v_mfma_f32_16x16x32_bf16 v[36:39], v[144:147], v[196:199], v[36:39]
	v_mfma_f32_16x16x32_bf16 v[32:35], v[160:163], v[196:199], v[32:35]
	v_mfma_f32_16x16x32_bf16 v[20:23], v[144:147], v[204:207], v[20:23]
	v_mfma_f32_16x16x32_bf16 v[16:19], v[160:163], v[204:207], v[16:19]
	v_mfma_f32_16x16x32_bf16 v[60:63], v[148:151], v[184:187], v[60:63]
	v_mfma_f32_16x16x32_bf16 v[56:59], v[164:167], v[184:187], v[56:59]
	v_mfma_f32_16x16x32_bf16 v[52:55], v[148:151], v[192:195], v[52:55]
	v_mfma_f32_16x16x32_bf16 v[48:51], v[164:167], v[192:195], v[48:51]
	v_mfma_f32_16x16x32_bf16 v[36:39], v[148:151], v[200:203], v[36:39]
	v_mfma_f32_16x16x32_bf16 v[32:35], v[164:167], v[200:203], v[32:35]
	v_mfma_f32_16x16x32_bf16 v[20:23], v[148:151], v[208:211], v[20:23]
	v_mfma_f32_16x16x32_bf16 v[16:19], v[164:167], v[208:211], v[16:19]
	s_barrier
	s_setprio 0
	s_add_i32 s1, s17, s85
	v_lshl_add_u64 v[144:145], v[234:235], 0, s[8:9]
	s_mov_b32 m0, s1
	s_nop 0
	global_load_lds_dwordx4 v[144:145], off
	v_lshl_add_u64 v[144:145], v[236:237], 0, s[8:9]
	s_add_i32 m0, s1, 0x2000
	s_nop 0
	global_load_lds_dwordx4 v[144:145], off
	s_waitcnt vmcnt(6)
	s_setprio 1
	s_barrier
	v_mfma_f32_16x16x32_bf16 v[44:47], v[212:215], v[168:171], v[44:47]
	v_mfma_f32_16x16x32_bf16 v[40:43], v[220:223], v[168:171], v[40:43]
	v_mfma_f32_16x16x32_bf16 v[28:31], v[212:215], v[188:191], v[28:31]
	v_mfma_f32_16x16x32_bf16 v[24:27], v[220:223], v[188:191], v[24:27]
	v_mfma_f32_16x16x32_bf16 v[12:15], v[212:215], v[196:199], v[12:15]
	v_mfma_f32_16x16x32_bf16 v[8:11], v[220:223], v[196:199], v[8:11]
	s_add_u32 vcc_lo, vcc_lo, 0x100
	v_mfma_f32_16x16x32_bf16 v[4:7], v[212:215], v[204:207], v[4:7]
	s_addc_u32 vcc_hi, vcc_hi, 0
	v_mfma_f32_16x16x32_bf16 v[0:3], v[220:223], v[204:207], v[0:3]
	s_add_u32 s96, s96, 0x100
	v_mfma_f32_16x16x32_bf16 v[44:47], v[216:219], v[184:187], v[44:47]
	s_addc_u32 s65, s65, 0
	v_mfma_f32_16x16x32_bf16 v[40:43], v[224:227], v[184:187], v[40:43]
	s_cmp_ge_u32 s0, s94
	v_mfma_f32_16x16x32_bf16 v[28:31], v[216:219], v[192:195], v[28:31]
	s_mov_b32 s34, s0
	v_mfma_f32_16x16x32_bf16 v[24:27], v[224:227], v[192:195], v[24:27]
	v_mfma_f32_16x16x32_bf16 v[12:15], v[216:219], v[200:203], v[12:15]
	v_mfma_f32_16x16x32_bf16 v[8:11], v[224:227], v[200:203], v[8:11]
	v_mfma_f32_16x16x32_bf16 v[4:7], v[216:219], v[208:211], v[4:7]
	v_mfma_f32_16x16x32_bf16 v[0:3], v[224:227], v[208:211], v[0:3]
	s_barrier
	s_setprio 0
	s_cbranch_scc0 .LBB0_100

; #define PG8_STAGE(bufoff, gbase, voff) do { _Pragma("unroll") for (int _i = 0; _i < 2; ++_i) \
;         __builtin_amdgcn_global_load_lds((const unsigned*)((const char*)(gbase) + (voff)[_i]), (LAS unsigned*)(lds + (bufoff) + ldsw + _i * 8192), 16, 0, 0); } while (0)
; #define PG8_LDA(dst, b, h) do { _Pragma("unroll") for (int m = 0; m < 4; ++m) _Pragma("unroll") for (int k = 0; k < 2; ++k) dst[m][k] = *(const LAS bf16x8*)(lds + PG8_SA(b, h) + aoff + m * 2048 + k * 1024); } while (0)
; #define PG8_LDB(dst, b, h) do { _Pragma("unroll") for (int n = 0; n < 2; ++n) _Pragma("unroll") for (int k = 0; k < 2; ++k) dst[n][k] = *(const LAS bf16x8*)(lds + PG8_SB(b, h) + boff + n * 2048 + k * 1024); } while (0)
; #define PG8_MMA(ai, bj, At, Bt) do { __builtin_amdgcn_s_setprio(1); _Pragma("unroll") for (int m = 0; m < 4; ++m) _Pragma("unroll") for (int n = 0; n < 2; ++n) _Pragma("unroll") for (int k = 0; k < 2; ++k) \
;         acc[ai][bj][m][n] = __builtin_amdgcn_mfma_f32_16x16x32_bf16(Bt[n][k], At[m][k], acc[ai][bj][m][n], 0, 0, 0); __builtin_amdgcn_s_setprio(0); } while (0)
; #define PG8_WAIT_L(n) asm volatile("s_waitcnt lgkmcnt(" #n ")" ::: "memory")
; template <class Epi, class Sched>
; __device__ __forceinline__ void gemm_phase(LAS unsigned char* lds, const Gemm g, const Sched& S, const Epi& E, int tid) {
;     ...
;         const bool has_next = S.next(ui + 1, nxt);
;         const char* nA = has_next ? (const char*)g.A + (size_t)nxt.pm * tstep : cA; const char* nB = has_next ? (const char*)g.Bt + (size_t)nxt.pn * tstep : cB;
;         for (int t = 0; t < nt; t += 2) {
;             const bool last = (t == nt - 2);
;             const char* a1 = cA + (size_t)(t + 1) * kstep;
;             const char* a2 = last ? nA : cA + (size_t)(t + 2) * kstep; const char* b2 = last ? nB : cB + (size_t)(t + 2) * kstep;
;             const char* a3 = a2 + kstep; const char* b3 = b2 + kstep;
;             PG8_LDB(B0, 0, 0); PG8_SCHED; PG8_LDA(At, 0, 0); PG8_STAGE(PG8_SA(1, 1), a1 + hstep, voffA);
;             PG8_WAIT_L(8); PG8_BAR; PG8_WAIT_L(0); PG8_MMA(0, 0, At, B0); PG8_BAR; PG8_SCHED;
;             PG8_LDB(B1, 0, 1); PG8_STAGE(PG8_SB(0, 0), b2, voffB);
;             PG8_BAR; PG8_WAIT_L(0); PG8_MMA(0, 1, At, B1); PG8_BAR;
;             PG8_LDA(At, 0, 1); PG8_STAGE(PG8_SA(0, 0), a2, voffA);
;             PG8_BAR; PG8_WAIT_L(0); PG8_MMA(1, 0, At, B0); PG8_BAR; PG8_SCHED;
.LBB0_114:
	s_ashr_i32 s25, s24, 31
	s_lshl_b64 s[0:1], s[24:25], 19
	v_cmp_lt_i64_e32 vcc, s[28:29], v[158:159]
	s_add_u32 s28, s26, s0
	s_addc_u32 s29, s27, s1
	s_and_b64 s[0:1], vcc, exec
	s_cselect_b32 s25, s29, s41
	s_cselect_b32 s53, s28, s40
	s_ashr_i32 s15, s14, 31
	s_lshl_b64 s[0:1], s[14:15], 19
	s_add_u32 s30, s19, s0
	s_addc_u32 s31, s44, s1
	s_and_b64 s[0:1], vcc, exec
	s_cselect_b32 s15, s31, s43
	s_cselect_b32 s55, s30, s42
	s_add_u32 s40, s40, 0x40080
	s_addc_u32 s41, s41, 0
	s_add_u32 s58, s42, 0x100
	s_addc_u32 s60, s43, 0
	s_mov_b32 s61, -2
	v_add_u32_e32 v240, 0x10000, v143
	ds_read_b128 v[138:141], v240
	ds_read_b128 v[146:149], v240 offset:1024
	ds_read_b128 v[150:153], v240 offset:2048
	ds_read_b128 v[160:163], v240 offset:3072
	v_lshl_add_u64 v[208:209], s[40:41], 0, v[134:135]
	s_add_i32 m0, s39, 0xc000
	ds_read_b128 v[164:167], v145
	ds_read_b128 v[184:187], v145 offset:2048
	ds_read_b128 v[192:195], v145 offset:4096
	ds_read_b128 v[200:203], v145 offset:6144
	global_load_lds_dwordx4 v[208:209], off
	s_waitcnt lgkmcnt(4)
	s_setprio 1
	s_barrier
	s_waitcnt lgkmcnt(0)
	v_mfma_f32_16x16x32_bf16 v[124:127], v[138:141], v[164:167], 0
	ds_read_b128 v[168:171], v145 offset:1024
	s_add_u32 s0, s40, 0xfffc0080
	v_mfma_f32_16x16x32_bf16 v[120:123], v[150:153], v[164:167], 0
	ds_read_b128 v[188:191], v145 offset:3072
	s_addc_u32 s1, s41, -1
	v_mfma_f32_16x16x32_bf16 v[108:111], v[138:141], v[184:187], 0
	ds_read_b128 v[196:199], v145 offset:5120
	s_add_i32 s17, 0, 0x10000
	v_mfma_f32_16x16x32_bf16 v[104:107], v[150:153], v[184:187], 0
	ds_read_b128 v[204:207], v145 offset:7168
	s_cmp_eq_u32 s61, 12
	v_mfma_f32_16x16x32_bf16 v[92:95], v[138:141], v[192:195], 0
	s_cselect_b32 s43, s25, s1
	v_mfma_f32_16x16x32_bf16 v[88:91], v[150:153], v[192:195], 0
	s_cselect_b32 s42, s53, s0
	v_mfma_f32_16x16x32_bf16 v[76:79], v[138:141], v[200:203], 0
	s_cselect_b32 s35, s15, s60
	v_mfma_f32_16x16x32_bf16 v[72:75], v[150:153], v[200:203], 0
	s_cselect_b32 s34, s55, s58
	s_waitcnt lgkmcnt(0)
	v_mfma_f32_16x16x32_bf16 v[124:127], v[146:149], v[168:171], v[124:127]
	s_add_i32 s63, 0, 0x14000
	v_add_u32_e32 v183, s63, v143
	v_mfma_f32_16x16x32_bf16 v[120:123], v[160:163], v[168:171], v[120:123]
	ds_read_b128 v[208:211], v183
	v_mfma_f32_16x16x32_bf16 v[108:111], v[146:149], v[188:191], v[108:111]
	ds_read_b128 v[212:215], v183 offset:1024
	v_mfma_f32_16x16x32_bf16 v[104:107], v[160:163], v[188:191], v[104:107]
	ds_read_b128 v[216:219], v183 offset:2048
	v_mfma_f32_16x16x32_bf16 v[92:95], v[146:149], v[196:199], v[92:95]
	ds_read_b128 v[220:223], v183 offset:3072
	v_mfma_f32_16x16x32_bf16 v[88:91], v[160:163], v[196:199], v[88:91]
	v_mfma_f32_16x16x32_bf16 v[76:79], v[146:149], v[204:207], v[76:79]
	v_mfma_f32_16x16x32_bf16 v[72:75], v[160:163], v[204:207], v[72:75]
	s_barrier
	s_setprio 0
	v_lshl_add_u64 v[238:239], s[40:41], 0, v[136:137]
	s_add_i32 m0, s39, 0xe000
	s_nop 0
	global_load_lds_dwordx4 v[238:239], off
	s_add_i32 s0, s17, s45
	v_lshl_add_u64 v[224:225], s[34:35], 0, v[154:155]
	s_mov_b32 m0, s0
	global_load_lds_dwordx4 v[224:225], off
	v_lshl_add_u64 v[226:227], s[34:35], 0, v[128:129]
	s_add_i32 m0, s0, 0x2000
	s_nop 0
	global_load_lds_dwordx4 v[226:227], off
	s_setprio 1
	s_barrier
	s_waitcnt lgkmcnt(0)
	v_mfma_f32_16x16x32_bf16 v[116:119], v[208:211], v[164:167], 0
	v_mfma_f32_16x16x32_bf16 v[112:115], v[216:219], v[164:167], 0
	v_mfma_f32_16x16x32_bf16 v[100:103], v[208:211], v[184:187], 0
	v_mfma_f32_16x16x32_bf16 v[96:99], v[216:219], v[184:187], 0
	v_mfma_f32_16x16x32_bf16 v[84:87], v[208:211], v[192:195], 0
	v_mfma_f32_16x16x32_bf16 v[80:83], v[216:219], v[192:195], 0
	s_mov_b32 m0, s39
	v_mfma_f32_16x16x32_bf16 v[68:71], v[208:211], v[200:203], 0
	v_lshl_add_u64 v[228:229], s[42:43], 0, v[132:133]
	v_mfma_f32_16x16x32_bf16 v[64:67], v[216:219], v[200:203], 0
	v_mfma_f32_16x16x32_bf16 v[116:119], v[212:215], v[168:171], v[116:119]
	v_mfma_f32_16x16x32_bf16 v[112:115], v[220:223], v[168:171], v[112:115]
	v_mfma_f32_16x16x32_bf16 v[100:103], v[212:215], v[188:191], v[100:103]
	v_mfma_f32_16x16x32_bf16 v[96:99], v[220:223], v[188:191], v[96:99]
	v_mfma_f32_16x16x32_bf16 v[84:87], v[212:215], v[196:199], v[84:87]
	v_mfma_f32_16x16x32_bf16 v[80:83], v[220:223], v[196:199], v[80:83]
	v_mfma_f32_16x16x32_bf16 v[68:71], v[212:215], v[204:207], v[68:71]
	v_mfma_f32_16x16x32_bf16 v[64:67], v[220:223], v[204:207], v[64:67]
	s_barrier
	s_setprio 0
	ds_read_b128 v[164:167], v145 offset:16384
	ds_read_b128 v[168:171], v145 offset:17408
	ds_read_b128 v[184:187], v145 offset:18432
	ds_read_b128 v[188:191], v145 offset:19456
	ds_read_b128 v[192:195], v145 offset:20480
	ds_read_b128 v[196:199], v145 offset:21504
	ds_read_b128 v[200:203], v145 offset:22528
	ds_read_b128 v[204:207], v145 offset:23552
	global_load_lds_dwordx4 v[228:229], off
	v_lshl_add_u64 v[230:231], s[42:43], 0, v[130:131]
	s_mov_b32 m0, s47
	s_nop 0
	global_load_lds_dwordx4 v[230:231], off
	s_setprio 1
	s_barrier
	s_waitcnt lgkmcnt(0)
	v_mfma_f32_16x16x32_bf16 v[60:63], v[138:141], v[164:167], 0
	v_mfma_f32_16x16x32_bf16 v[56:59], v[150:153], v[164:167], 0
	v_mfma_f32_16x16x32_bf16 v[44:47], v[138:141], v[184:187], 0
	v_mfma_f32_16x16x32_bf16 v[40:43], v[150:153], v[184:187], 0
	v_mfma_f32_16x16x32_bf16 v[28:31], v[138:141], v[192:195], 0
	v_mfma_f32_16x16x32_bf16 v[24:27], v[150:153], v[192:195], 0
	v_mfma_f32_16x16x32_bf16 v[12:15], v[138:141], v[200:203], 0
	v_mfma_f32_16x16x32_bf16 v[8:11], v[150:153], v[200:203], 0
	v_mfma_f32_16x16x32_bf16 v[60:63], v[146:149], v[168:171], v[60:63]
	v_mfma_f32_16x16x32_bf16 v[56:59], v[160:163], v[168:171], v[56:59]
	v_mfma_f32_16x16x32_bf16 v[44:47], v[146:149], v[188:191], v[44:47]
	v_mfma_f32_16x16x32_bf16 v[40:43], v[160:163], v[188:191], v[40:43]
	v_mfma_f32_16x16x32_bf16 v[28:31], v[146:149], v[196:199], v[28:31]
	v_mfma_f32_16x16x32_bf16 v[24:27], v[160:163], v[196:199], v[24:27]
	v_mfma_f32_16x16x32_bf16 v[12:15], v[146:149], v[204:207], v[12:15]
	v_mfma_f32_16x16x32_bf16 v[8:11], v[160:163], v[204:207], v[8:11]
	s_barrier
; #define PG8_STAGE(bufoff, gbase, voff) do { _Pragma("unroll") for (int _i = 0; _i < 2; ++_i) \
;         __builtin_amdgcn_global_load_lds((const unsigned*)((const char*)(gbase) + (voff)[_i]), (LAS unsigned*)(lds + (bufoff) + ldsw + _i * 8192), 16, 0, 0); } while (0)
; #define PG8_LDA(dst, b, h) do { _Pragma("unroll") for (int m = 0; m < 4; ++m) _Pragma("unroll") for (int k = 0; k < 2; ++k) dst[m][k] = *(const LAS bf16x8*)(lds + PG8_SA(b, h) + aoff + m * 2048 + k * 1024); } while (0)
; #define PG8_LDB(dst, b, h) do { _Pragma("unroll") for (int n = 0; n < 2; ++n) _Pragma("unroll") for (int k = 0; k < 2; ++k) dst[n][k] = *(const LAS bf16x8*)(lds + PG8_SB(b, h) + boff + n * 2048 + k * 1024); } while (0)
; #define PG8_MMA(ai, bj, At, Bt) do { __builtin_amdgcn_s_setprio(1); _Pragma("unroll") for (int m = 0; m < 4; ++m) _Pragma("unroll") for (int n = 0; n < 2; ++n) _Pragma("unroll") for (int k = 0; k < 2; ++k) \
;         acc[ai][bj][m][n] = __builtin_amdgcn_mfma_f32_16x16x32_bf16(Bt[n][k], At[m][k], acc[ai][bj][m][n], 0, 0, 0); __builtin_amdgcn_s_setprio(0); } while (0)
; #define PG8_WAIT_V(n) asm volatile("s_waitcnt vmcnt(" #n ")" ::: "memory")
; #define PG8_WAIT_L(n) asm volatile("s_waitcnt lgkmcnt(" #n ")" ::: "memory")
; #define PG8_BAR __builtin_amdgcn_s_barrier()
; #define PG8_SCHED __builtin_amdgcn_sched_barrier(0)
; template <class Epi, class Sched>
; __device__ __forceinline__ void gemm_phase(LAS unsigned char* lds, const Gemm g, const Sched& S, const Epi& E, int tid) {
;     ...
;             PG8_STAGE(PG8_SB(0, 1), b2 + hstep, voffB);
;             PG8_WAIT_V(6); PG8_BAR; PG8_MMA(1, 1, At, B1); PG8_BAR;
;             PG8_LDB(B0, 1, 0); PG8_SCHED; PG8_LDA(At, 1, 0); PG8_STAGE(PG8_SA(0, 1), a2 + hstep, voffA);
;             PG8_WAIT_L(8); PG8_BAR; PG8_WAIT_L(0); PG8_MMA(0, 0, At, B0); PG8_BAR; PG8_SCHED;
;             PG8_LDB(B1, 1, 1); PG8_STAGE(PG8_SB(1, 0), b3, voffB);
;             PG8_BAR; PG8_WAIT_L(0); PG8_MMA(0, 1, At, B1); PG8_BAR;
;             PG8_LDA(At, 1, 1); PG8_STAGE(PG8_SA(1, 0), a3, voffA);
;             PG8_BAR; PG8_WAIT_L(0); PG8_MMA(1, 0, At, B0); PG8_BAR; PG8_SCHED;
	s_setprio 0
	s_add_u32 s0, s34, 0x40000
	s_addc_u32 s1, s35, 0
	s_add_i32 s17, s63, s45
	v_lshl_add_u64 v[138:139], s[0:1], 0, v[154:155]
	s_mov_b32 m0, s17
	s_nop 0
	global_load_lds_dwordx4 v[138:139], off
	v_lshl_add_u64 v[138:139], s[0:1], 0, v[128:129]
	s_add_i32 m0, s17, 0x2000
	s_nop 0
	global_load_lds_dwordx4 v[138:139], off
	s_waitcnt vmcnt(16)
	s_setprio 1
	s_barrier
	v_mfma_f32_16x16x32_bf16 v[52:55], v[208:211], v[164:167], 0
	v_mfma_f32_16x16x32_bf16 v[48:51], v[216:219], v[164:167], 0
	v_mfma_f32_16x16x32_bf16 v[36:39], v[208:211], v[184:187], 0
	v_mfma_f32_16x16x32_bf16 v[32:35], v[216:219], v[184:187], 0
	v_mfma_f32_16x16x32_bf16 v[20:23], v[208:211], v[192:195], 0
	v_mfma_f32_16x16x32_bf16 v[16:19], v[216:219], v[192:195], 0
	s_add_i32 s17, 0, 0x18000
	v_mfma_f32_16x16x32_bf16 v[4:7], v[208:211], v[200:203], 0
	v_add_u32_e32 v160, s17, v143
	v_mfma_f32_16x16x32_bf16 v[0:3], v[216:219], v[200:203], 0
	v_mfma_f32_16x16x32_bf16 v[52:55], v[212:215], v[168:171], v[52:55]
	v_mfma_f32_16x16x32_bf16 v[48:51], v[220:223], v[168:171], v[48:51]
	v_mfma_f32_16x16x32_bf16 v[36:39], v[212:215], v[188:191], v[36:39]
	v_mfma_f32_16x16x32_bf16 v[32:35], v[220:223], v[188:191], v[32:35]
	v_mfma_f32_16x16x32_bf16 v[20:23], v[212:215], v[196:199], v[20:23]
	v_mfma_f32_16x16x32_bf16 v[16:19], v[220:223], v[196:199], v[16:19]
	v_mfma_f32_16x16x32_bf16 v[4:7], v[212:215], v[204:207], v[4:7]
	v_mfma_f32_16x16x32_bf16 v[0:3], v[220:223], v[204:207], v[0:3]
	s_barrier
	s_setprio 0
	ds_read_b128 v[138:141], v160
	ds_read_b128 v[146:149], v160 offset:1024
	ds_read_b128 v[150:153], v160 offset:2048
	ds_read_b128 v[160:163], v160 offset:3072
	s_add_u32 s0, s42, 0x40000
	s_addc_u32 s1, s43, 0
	s_mov_b32 m0, s48
	v_lshl_add_u64 v[208:209], s[0:1], 0, v[132:133]
	ds_read_b128 v[164:167], v145 offset:32768
	ds_read_b128 v[184:187], v145 offset:34816
	ds_read_b128 v[192:195], v145 offset:36864
	ds_read_b128 v[200:203], v145 offset:38912
	global_load_lds_dwordx4 v[208:209], off
	s_waitcnt lgkmcnt(4)
	s_setprio 1
	s_barrier
	s_waitcnt lgkmcnt(0)
	v_mfma_f32_16x16x32_bf16 v[124:127], v[138:141], v[164:167], v[124:127]
	ds_read_b128 v[168:171], v145 offset:33792
	v_mfma_f32_16x16x32_bf16 v[120:123], v[150:153], v[164:167], v[120:123]
	ds_read_b128 v[188:191], v145 offset:35840
	v_mfma_f32_16x16x32_bf16 v[108:111], v[138:141], v[184:187], v[108:111]
	ds_read_b128 v[196:199], v145 offset:37888
	v_mfma_f32_16x16x32_bf16 v[104:107], v[150:153], v[184:187], v[104:107]
	ds_read_b128 v[204:207], v145 offset:39936
	v_mfma_f32_16x16x32_bf16 v[92:95], v[138:141], v[192:195], v[92:95]
	v_mfma_f32_16x16x32_bf16 v[88:91], v[150:153], v[192:195], v[88:91]
	v_mfma_f32_16x16x32_bf16 v[76:79], v[138:141], v[200:203], v[76:79]
	v_mfma_f32_16x16x32_bf16 v[72:75], v[150:153], v[200:203], v[72:75]
	s_waitcnt lgkmcnt(0)
	v_mfma_f32_16x16x32_bf16 v[124:127], v[146:149], v[168:171], v[124:127]
	s_add_i32 s42, 0, 0x1c000
	v_add_u32_e32 v183, s42, v143
	v_mfma_f32_16x16x32_bf16 v[120:123], v[160:163], v[168:171], v[120:123]
	ds_read_b128 v[208:211], v183
	v_mfma_f32_16x16x32_bf16 v[108:111], v[146:149], v[188:191], v[108:111]
	ds_read_b128 v[212:215], v183 offset:1024
	v_mfma_f32_16x16x32_bf16 v[104:107], v[160:163], v[188:191], v[104:107]
	ds_read_b128 v[216:219], v183 offset:2048
	v_mfma_f32_16x16x32_bf16 v[92:95], v[146:149], v[196:199], v[92:95]
	ds_read_b128 v[220:223], v183 offset:3072
	v_mfma_f32_16x16x32_bf16 v[88:91], v[160:163], v[196:199], v[88:91]
	v_mfma_f32_16x16x32_bf16 v[76:79], v[146:149], v[204:207], v[76:79]
	v_mfma_f32_16x16x32_bf16 v[72:75], v[160:163], v[204:207], v[72:75]
	s_barrier
	s_setprio 0
	v_lshl_add_u64 v[238:239], s[0:1], 0, v[130:131]
	s_mov_b32 m0, s49
	s_nop 0
	global_load_lds_dwordx4 v[238:239], off
	s_add_i32 s0, s17, s45
	v_lshl_add_u64 v[224:225], v[224:225], 0, s[8:9]
	s_mov_b32 m0, s0
	global_load_lds_dwordx4 v[224:225], off
	v_lshl_add_u64 v[224:225], v[226:227], 0, s[8:9]
	s_add_i32 m0, s0, 0x2000
	s_nop 0
	global_load_lds_dwordx4 v[224:225], off
	s_waitcnt vmcnt(10)
	s_setprio 1
	s_barrier
	s_waitcnt lgkmcnt(0)
	v_mfma_f32_16x16x32_bf16 v[116:119], v[208:211], v[164:167], v[116:119]
	v_mfma_f32_16x16x32_bf16 v[112:115], v[216:219], v[164:167], v[112:115]
	v_mfma_f32_16x16x32_bf16 v[100:103], v[208:211], v[184:187], v[100:103]
	v_mfma_f32_16x16x32_bf16 v[96:99], v[216:219], v[184:187], v[96:99]
	v_mfma_f32_16x16x32_bf16 v[84:87], v[208:211], v[192:195], v[84:87]
	v_mfma_f32_16x16x32_bf16 v[80:83], v[216:219], v[192:195], v[80:83]
	s_mov_b32 m0, s6
	v_mfma_f32_16x16x32_bf16 v[68:71], v[208:211], v[200:203], v[68:71]
	v_lshl_add_u64 v[224:225], v[228:229], 0, s[8:9]
	v_mfma_f32_16x16x32_bf16 v[64:67], v[216:219], v[200:203], v[64:67]
	v_mfma_f32_16x16x32_bf16 v[116:119], v[212:215], v[168:171], v[116:119]
	v_mfma_f32_16x16x32_bf16 v[112:115], v[220:223], v[168:171], v[112:115]
	v_mfma_f32_16x16x32_bf16 v[100:103], v[212:215], v[188:191], v[100:103]
	v_mfma_f32_16x16x32_bf16 v[96:99], v[220:223], v[188:191], v[96:99]
	v_mfma_f32_16x16x32_bf16 v[84:87], v[212:215], v[196:199], v[84:87]
	v_mfma_f32_16x16x32_bf16 v[80:83], v[220:223], v[196:199], v[80:83]
	v_mfma_f32_16x16x32_bf16 v[68:71], v[212:215], v[204:207], v[68:71]
	v_mfma_f32_16x16x32_bf16 v[64:67], v[220:223], v[204:207], v[64:67]
	s_barrier
	s_setprio 0
	ds_read_b128 v[164:167], v145 offset:49152
	ds_read_b128 v[168:171], v145 offset:50176
	ds_read_b128 v[184:187], v145 offset:51200
	ds_read_b128 v[188:191], v145 offset:52224
	ds_read_b128 v[192:195], v145 offset:53248
	ds_read_b128 v[196:199], v145 offset:54272
	ds_read_b128 v[200:203], v145 offset:55296
	ds_read_b128 v[204:207], v145 offset:56320
	global_load_lds_dwordx4 v[224:225], off
	v_lshl_add_u64 v[224:225], v[230:231], 0, s[8:9]
	s_mov_b32 m0, s50
	s_nop 0
	global_load_lds_dwordx4 v[224:225], off
	s_setprio 1
	s_barrier
; #define PG8_STAGE(bufoff, gbase, voff) do { _Pragma("unroll") for (int _i = 0; _i < 2; ++_i) \
;         __builtin_amdgcn_global_load_lds((const unsigned*)((const char*)(gbase) + (voff)[_i]), (LAS unsigned*)(lds + (bufoff) + ldsw + _i * 8192), 16, 0, 0); } while (0)
; #define PG8_LDA(dst, b, h) do { _Pragma("unroll") for (int m = 0; m < 4; ++m) _Pragma("unroll") for (int k = 0; k < 2; ++k) dst[m][k] = *(const LAS bf16x8*)(lds + PG8_SA(b, h) + aoff + m * 2048 + k * 1024); } while (0)
; #define PG8_LDB(dst, b, h) do { _Pragma("unroll") for (int n = 0; n < 2; ++n) _Pragma("unroll") for (int k = 0; k < 2; ++k) dst[n][k] = *(const LAS bf16x8*)(lds + PG8_SB(b, h) + boff + n * 2048 + k * 1024); } while (0)
; #define PG8_MMA(ai, bj, At, Bt) do { __builtin_amdgcn_s_setprio(1); _Pragma("unroll") for (int m = 0; m < 4; ++m) _Pragma("unroll") for (int n = 0; n < 2; ++n) _Pragma("unroll") for (int k = 0; k < 2; ++k) \
;         acc[ai][bj][m][n] = __builtin_amdgcn_mfma_f32_16x16x32_bf16(Bt[n][k], At[m][k], acc[ai][bj][m][n], 0, 0, 0); __builtin_amdgcn_s_setprio(0); } while (0)
; #define PG8_WAIT_V(n) asm volatile("s_waitcnt vmcnt(" #n ")" ::: "memory")
; #define PG8_WAIT_L(n) asm volatile("s_waitcnt lgkmcnt(" #n ")" ::: "memory")
; #define PG8_BAR __builtin_amdgcn_s_barrier()
; #define PG8_SCHED __builtin_amdgcn_sched_barrier(0)
; template <class Epi, class Sched>
; __device__ __forceinline__ void gemm_phase(LAS unsigned char* lds, const Gemm g, const Sched& S, const Epi& E, int tid) {
;     ...
;         for (int t = 0; t < nt; t += 2) {
;             const bool last = (t == nt - 2);
;             const char* a1 = cA + (size_t)(t + 1) * kstep;
;             const char* a2 = last ? nA : cA + (size_t)(t + 2) * kstep; const char* b2 = last ? nB : cB + (size_t)(t + 2) * kstep;
;             const char* a3 = a2 + kstep; const char* b3 = b2 + kstep;
;             PG8_LDB(B0, 0, 0); PG8_SCHED; PG8_LDA(At, 0, 0); PG8_STAGE(PG8_SA(1, 1), a1 + hstep, voffA);
;             PG8_WAIT_L(8); PG8_BAR; PG8_WAIT_L(0); PG8_MMA(0, 0, At, B0); PG8_BAR; PG8_SCHED;
;             PG8_LDB(B1, 0, 1); PG8_STAGE(PG8_SB(0, 0), b2, voffB);
;     ...
;             PG8_BAR; PG8_WAIT_L(0); PG8_MMA(1, 0, At, B0); PG8_BAR; PG8_SCHED;
;             PG8_STAGE(PG8_SB(1, 1), b3 + hstep, voffB);
;             PG8_WAIT_V(6); PG8_BAR; PG8_MMA(1, 1, At, B1); PG8_BAR;
	s_waitcnt lgkmcnt(0)
	v_mfma_f32_16x16x32_bf16 v[60:63], v[138:141], v[164:167], v[60:63]
	v_mfma_f32_16x16x32_bf16 v[56:59], v[150:153], v[164:167], v[56:59]
	v_mfma_f32_16x16x32_bf16 v[44:47], v[138:141], v[184:187], v[44:47]
	v_mfma_f32_16x16x32_bf16 v[40:43], v[150:153], v[184:187], v[40:43]
	v_mfma_f32_16x16x32_bf16 v[28:31], v[138:141], v[192:195], v[28:31]
	v_mfma_f32_16x16x32_bf16 v[24:27], v[150:153], v[192:195], v[24:27]
	v_mfma_f32_16x16x32_bf16 v[12:15], v[138:141], v[200:203], v[12:15]
	v_mfma_f32_16x16x32_bf16 v[8:11], v[150:153], v[200:203], v[8:11]
	v_mfma_f32_16x16x32_bf16 v[60:63], v[146:149], v[168:171], v[60:63]
	v_mfma_f32_16x16x32_bf16 v[56:59], v[160:163], v[168:171], v[56:59]
	v_mfma_f32_16x16x32_bf16 v[44:47], v[146:149], v[188:191], v[44:47]
	v_mfma_f32_16x16x32_bf16 v[40:43], v[160:163], v[188:191], v[40:43]
	v_mfma_f32_16x16x32_bf16 v[28:31], v[146:149], v[196:199], v[28:31]
	v_mfma_f32_16x16x32_bf16 v[24:27], v[160:163], v[196:199], v[24:27]
	v_mfma_f32_16x16x32_bf16 v[12:15], v[146:149], v[204:207], v[12:15]
	v_mfma_f32_16x16x32_bf16 v[8:11], v[160:163], v[204:207], v[8:11]
	s_barrier
	s_setprio 0
	s_add_u32 s0, s34, 0x40080
	s_addc_u32 s1, s35, 0
	s_add_i32 s17, s42, s45
	v_lshl_add_u64 v[138:139], s[0:1], 0, v[154:155]
	s_mov_b32 m0, s17
	s_nop 0
	global_load_lds_dwordx4 v[138:139], off
	v_lshl_add_u64 v[138:139], s[0:1], 0, v[128:129]
	s_add_i32 m0, s17, 0x2000
	s_nop 0
	global_load_lds_dwordx4 v[138:139], off
	s_waitcnt vmcnt(6)
	s_setprio 1
	s_barrier
	v_mfma_f32_16x16x32_bf16 v[52:55], v[208:211], v[164:167], v[52:55]
	v_mfma_f32_16x16x32_bf16 v[48:51], v[216:219], v[164:167], v[48:51]
	v_mfma_f32_16x16x32_bf16 v[36:39], v[208:211], v[184:187], v[36:39]
	v_mfma_f32_16x16x32_bf16 v[32:35], v[216:219], v[184:187], v[32:35]
	v_mfma_f32_16x16x32_bf16 v[20:23], v[208:211], v[192:195], v[20:23]
	v_mfma_f32_16x16x32_bf16 v[16:19], v[216:219], v[192:195], v[16:19]
	s_add_i32 s61, s61, 2
	v_mfma_f32_16x16x32_bf16 v[4:7], v[208:211], v[200:203], v[4:7]
	s_add_u32 s40, s40, 0x100
	v_mfma_f32_16x16x32_bf16 v[0:3], v[216:219], v[200:203], v[0:3]
	s_addc_u32 s41, s41, 0
	v_mfma_f32_16x16x32_bf16 v[52:55], v[212:215], v[168:171], v[52:55]
	s_add_u32 s58, s58, 0x100
	v_mfma_f32_16x16x32_bf16 v[48:51], v[220:223], v[168:171], v[48:51]
	s_addc_u32 s60, s60, 0
	v_mfma_f32_16x16x32_bf16 v[36:39], v[212:215], v[188:191], v[36:39]
	s_cmp_gt_u32 s61, 13
	v_mfma_f32_16x16x32_bf16 v[32:35], v[220:223], v[188:191], v[32:35]
	v_mfma_f32_16x16x32_bf16 v[20:23], v[212:215], v[196:199], v[20:23]
	v_mfma_f32_16x16x32_bf16 v[16:19], v[220:223], v[196:199], v[16:19]
	v_mfma_f32_16x16x32_bf16 v[4:7], v[212:215], v[204:207], v[4:7]
	v_mfma_f32_16x16x32_bf16 v[0:3], v[220:223], v[204:207], v[0:3]
	s_barrier
	s_setprio 0
	s_cbranch_scc1 .Lpeel_exit_swiglu
.LBB0_115:
	ds_read_b128 v[138:141], v240
	ds_read_b128 v[146:149], v240 offset:1024
	ds_read_b128 v[150:153], v240 offset:2048
	ds_read_b128 v[160:163], v240 offset:3072
	v_lshl_add_u64 v[208:209], s[40:41], 0, v[134:135]
	s_add_i32 m0, s39, 0xc000
	ds_read_b128 v[164:167], v145
	ds_read_b128 v[184:187], v145 offset:2048
	ds_read_b128 v[192:195], v145 offset:4096
	ds_read_b128 v[200:203], v145 offset:6144
	global_load_lds_dwordx4 v[208:209], off
	s_waitcnt lgkmcnt(4)
	s_setprio 1
	s_barrier
	s_waitcnt lgkmcnt(0)
	v_mfma_f32_16x16x32_bf16 v[124:127], v[138:141], v[164:167], v[124:127]
	ds_read_b128 v[168:171], v145 offset:1024
	s_add_u32 s0, s40, 0xfffc0080
	v_mfma_f32_16x16x32_bf16 v[120:123], v[150:153], v[164:167], v[120:123]
	ds_read_b128 v[188:191], v145 offset:3072
	s_addc_u32 s1, s41, -1
	v_mfma_f32_16x16x32_bf16 v[108:111], v[138:141], v[184:187], v[108:111]
	ds_read_b128 v[196:199], v145 offset:5120
	s_add_i32 s17, 0, 0x10000
	v_mfma_f32_16x16x32_bf16 v[104:107], v[150:153], v[184:187], v[104:107]
	ds_read_b128 v[204:207], v145 offset:7168
	s_cmp_eq_u32 s61, 12
	v_mfma_f32_16x16x32_bf16 v[92:95], v[138:141], v[192:195], v[92:95]
	s_cselect_b32 s43, s25, s1
	v_mfma_f32_16x16x32_bf16 v[88:91], v[150:153], v[192:195], v[88:91]
	s_cselect_b32 s42, s53, s0
	v_mfma_f32_16x16x32_bf16 v[76:79], v[138:141], v[200:203], v[76:79]
	s_cselect_b32 s35, s15, s60
	v_mfma_f32_16x16x32_bf16 v[72:75], v[150:153], v[200:203], v[72:75]
	s_cselect_b32 s34, s55, s58
	s_waitcnt lgkmcnt(0)
	v_mfma_f32_16x16x32_bf16 v[124:127], v[146:149], v[168:171], v[124:127]
	s_add_i32 s63, 0, 0x14000
	v_add_u32_e32 v183, s63, v143
	v_mfma_f32_16x16x32_bf16 v[120:123], v[160:163], v[168:171], v[120:123]
	ds_read_b128 v[208:211], v183
	v_mfma_f32_16x16x32_bf16 v[108:111], v[146:149], v[188:191], v[108:111]
	ds_read_b128 v[212:215], v183 offset:1024
	v_mfma_f32_16x16x32_bf16 v[104:107], v[160:163], v[188:191], v[104:107]
	ds_read_b128 v[216:219], v183 offset:2048
	v_mfma_f32_16x16x32_bf16 v[92:95], v[146:149], v[196:199], v[92:95]
	ds_read_b128 v[220:223], v183 offset:3072
	v_mfma_f32_16x16x32_bf16 v[88:91], v[160:163], v[196:199], v[88:91]
	v_mfma_f32_16x16x32_bf16 v[76:79], v[146:149], v[204:207], v[76:79]
	v_mfma_f32_16x16x32_bf16 v[72:75], v[160:163], v[204:207], v[72:75]
	s_barrier
	s_setprio 0
	v_lshl_add_u64 v[238:239], s[40:41], 0, v[136:137]
	s_add_i32 m0, s39, 0xe000
	s_nop 0
	global_load_lds_dwordx4 v[238:239], off
	s_add_i32 s0, s17, s45
	v_lshl_add_u64 v[224:225], s[34:35], 0, v[154:155]
	s_mov_b32 m0, s0
	global_load_lds_dwordx4 v[224:225], off
	v_lshl_add_u64 v[226:227], s[34:35], 0, v[128:129]
	s_add_i32 m0, s0, 0x2000
	s_nop 0
	global_load_lds_dwordx4 v[226:227], off
	s_setprio 1
	s_barrier
; #define PG8_STAGE(bufoff, gbase, voff) do { _Pragma("unroll") for (int _i = 0; _i < 2; ++_i) \
;         __builtin_amdgcn_global_load_lds((const unsigned*)((const char*)(gbase) + (voff)[_i]), (LAS unsigned*)(lds + (bufoff) + ldsw + _i * 8192), 16, 0, 0); } while (0)
; #define PG8_LDA(dst, b, h) do { _Pragma("unroll") for (int m = 0; m < 4; ++m) _Pragma("unroll") for (int k = 0; k < 2; ++k) dst[m][k] = *(const LAS bf16x8*)(lds + PG8_SA(b, h) + aoff + m * 2048 + k * 1024); } while (0)
; #define PG8_LDB(dst, b, h) do { _Pragma("unroll") for (int n = 0; n < 2; ++n) _Pragma("unroll") for (int k = 0; k < 2; ++k) dst[n][k] = *(const LAS bf16x8*)(lds + PG8_SB(b, h) + boff + n * 2048 + k * 1024); } while (0)
; #define PG8_MMA(ai, bj, At, Bt) do { __builtin_amdgcn_s_setprio(1); _Pragma("unroll") for (int m = 0; m < 4; ++m) _Pragma("unroll") for (int n = 0; n < 2; ++n) _Pragma("unroll") for (int k = 0; k < 2; ++k) \
;         acc[ai][bj][m][n] = __builtin_amdgcn_mfma_f32_16x16x32_bf16(Bt[n][k], At[m][k], acc[ai][bj][m][n], 0, 0, 0); __builtin_amdgcn_s_setprio(0); } while (0)
; #define PG8_WAIT_V(n) asm volatile("s_waitcnt vmcnt(" #n ")" ::: "memory")
; #define PG8_WAIT_L(n) asm volatile("s_waitcnt lgkmcnt(" #n ")" ::: "memory")
; #define PG8_BAR __builtin_amdgcn_s_barrier()
; #define PG8_SCHED __builtin_amdgcn_sched_barrier(0)
; template <class Epi, class Sched>
; __device__ __forceinline__ void gemm_phase(LAS unsigned char* lds, const Gemm g, const Sched& S, const Epi& E, int tid) {
;     ...
;             PG8_BAR; PG8_WAIT_L(0); PG8_MMA(0, 1, At, B1); PG8_BAR;
;             PG8_LDA(At, 0, 1); PG8_STAGE(PG8_SA(0, 0), a2, voffA);
;             PG8_BAR; PG8_WAIT_L(0); PG8_MMA(1, 0, At, B0); PG8_BAR; PG8_SCHED;
;             PG8_STAGE(PG8_SB(0, 1), b2 + hstep, voffB);
;             PG8_WAIT_V(6); PG8_BAR; PG8_MMA(1, 1, At, B1); PG8_BAR;
;             PG8_LDB(B0, 1, 0); PG8_SCHED; PG8_LDA(At, 1, 0); PG8_STAGE(PG8_SA(0, 1), a2 + hstep, voffA);
	s_waitcnt lgkmcnt(0)
	v_mfma_f32_16x16x32_bf16 v[116:119], v[208:211], v[164:167], v[116:119]
	v_mfma_f32_16x16x32_bf16 v[112:115], v[216:219], v[164:167], v[112:115]
	v_mfma_f32_16x16x32_bf16 v[100:103], v[208:211], v[184:187], v[100:103]
	v_mfma_f32_16x16x32_bf16 v[96:99], v[216:219], v[184:187], v[96:99]
	v_mfma_f32_16x16x32_bf16 v[84:87], v[208:211], v[192:195], v[84:87]
	v_mfma_f32_16x16x32_bf16 v[80:83], v[216:219], v[192:195], v[80:83]
	s_mov_b32 m0, s39
	v_mfma_f32_16x16x32_bf16 v[68:71], v[208:211], v[200:203], v[68:71]
	v_lshl_add_u64 v[228:229], s[42:43], 0, v[132:133]
	v_mfma_f32_16x16x32_bf16 v[64:67], v[216:219], v[200:203], v[64:67]
	v_mfma_f32_16x16x32_bf16 v[116:119], v[212:215], v[168:171], v[116:119]
	v_mfma_f32_16x16x32_bf16 v[112:115], v[220:223], v[168:171], v[112:115]
	v_mfma_f32_16x16x32_bf16 v[100:103], v[212:215], v[188:191], v[100:103]
	v_mfma_f32_16x16x32_bf16 v[96:99], v[220:223], v[188:191], v[96:99]
	v_mfma_f32_16x16x32_bf16 v[84:87], v[212:215], v[196:199], v[84:87]
	v_mfma_f32_16x16x32_bf16 v[80:83], v[220:223], v[196:199], v[80:83]
	v_mfma_f32_16x16x32_bf16 v[68:71], v[212:215], v[204:207], v[68:71]
	v_mfma_f32_16x16x32_bf16 v[64:67], v[220:223], v[204:207], v[64:67]
	s_barrier
	s_setprio 0
	ds_read_b128 v[164:167], v145 offset:16384
	ds_read_b128 v[168:171], v145 offset:17408
	ds_read_b128 v[184:187], v145 offset:18432
	ds_read_b128 v[188:191], v145 offset:19456
	ds_read_b128 v[192:195], v145 offset:20480
	ds_read_b128 v[196:199], v145 offset:21504
	ds_read_b128 v[200:203], v145 offset:22528
	ds_read_b128 v[204:207], v145 offset:23552
	global_load_lds_dwordx4 v[228:229], off
	v_lshl_add_u64 v[230:231], s[42:43], 0, v[130:131]
	s_mov_b32 m0, s47
	s_nop 0
	global_load_lds_dwordx4 v[230:231], off
	s_setprio 1
	s_barrier
	s_waitcnt lgkmcnt(0)
	v_mfma_f32_16x16x32_bf16 v[60:63], v[138:141], v[164:167], v[60:63]
	v_mfma_f32_16x16x32_bf16 v[56:59], v[150:153], v[164:167], v[56:59]
	v_mfma_f32_16x16x32_bf16 v[44:47], v[138:141], v[184:187], v[44:47]
	v_mfma_f32_16x16x32_bf16 v[40:43], v[150:153], v[184:187], v[40:43]
	v_mfma_f32_16x16x32_bf16 v[28:31], v[138:141], v[192:195], v[28:31]
	v_mfma_f32_16x16x32_bf16 v[24:27], v[150:153], v[192:195], v[24:27]
	v_mfma_f32_16x16x32_bf16 v[12:15], v[138:141], v[200:203], v[12:15]
	v_mfma_f32_16x16x32_bf16 v[8:11], v[150:153], v[200:203], v[8:11]
	v_mfma_f32_16x16x32_bf16 v[60:63], v[146:149], v[168:171], v[60:63]
	v_mfma_f32_16x16x32_bf16 v[56:59], v[160:163], v[168:171], v[56:59]
	v_mfma_f32_16x16x32_bf16 v[44:47], v[146:149], v[188:191], v[44:47]
	v_mfma_f32_16x16x32_bf16 v[40:43], v[160:163], v[188:191], v[40:43]
	v_mfma_f32_16x16x32_bf16 v[28:31], v[146:149], v[196:199], v[28:31]
	v_mfma_f32_16x16x32_bf16 v[24:27], v[160:163], v[196:199], v[24:27]
	v_mfma_f32_16x16x32_bf16 v[12:15], v[146:149], v[204:207], v[12:15]
	v_mfma_f32_16x16x32_bf16 v[8:11], v[160:163], v[204:207], v[8:11]
	s_barrier
	s_setprio 0
	s_add_u32 s0, s34, 0x40000
	s_addc_u32 s1, s35, 0
	s_add_i32 s17, s63, s45
	v_lshl_add_u64 v[138:139], s[0:1], 0, v[154:155]
	s_mov_b32 m0, s17
	s_nop 0
	global_load_lds_dwordx4 v[138:139], off
	v_lshl_add_u64 v[138:139], s[0:1], 0, v[128:129]
	s_add_i32 m0, s17, 0x2000
	s_nop 0
	global_load_lds_dwordx4 v[138:139], off
	s_waitcnt vmcnt(6)
	s_setprio 1
	s_barrier
	v_mfma_f32_16x16x32_bf16 v[52:55], v[208:211], v[164:167], v[52:55]
	v_mfma_f32_16x16x32_bf16 v[48:51], v[216:219], v[164:167], v[48:51]
	v_mfma_f32_16x16x32_bf16 v[36:39], v[208:211], v[184:187], v[36:39]
	v_mfma_f32_16x16x32_bf16 v[32:35], v[216:219], v[184:187], v[32:35]
	v_mfma_f32_16x16x32_bf16 v[20:23], v[208:211], v[192:195], v[20:23]
	v_mfma_f32_16x16x32_bf16 v[16:19], v[216:219], v[192:195], v[16:19]
	s_add_i32 s17, 0, 0x18000
	v_mfma_f32_16x16x32_bf16 v[4:7], v[208:211], v[200:203], v[4:7]
	v_add_u32_e32 v160, s17, v143
	v_mfma_f32_16x16x32_bf16 v[0:3], v[216:219], v[200:203], v[0:3]
	v_mfma_f32_16x16x32_bf16 v[52:55], v[212:215], v[168:171], v[52:55]
	v_mfma_f32_16x16x32_bf16 v[48:51], v[220:223], v[168:171], v[48:51]
	v_mfma_f32_16x16x32_bf16 v[36:39], v[212:215], v[188:191], v[36:39]
	v_mfma_f32_16x16x32_bf16 v[32:35], v[220:223], v[188:191], v[32:35]
	v_mfma_f32_16x16x32_bf16 v[20:23], v[212:215], v[196:199], v[20:23]
	v_mfma_f32_16x16x32_bf16 v[16:19], v[220:223], v[196:199], v[16:19]
	v_mfma_f32_16x16x32_bf16 v[4:7], v[212:215], v[204:207], v[4:7]
	v_mfma_f32_16x16x32_bf16 v[0:3], v[220:223], v[204:207], v[0:3]
	s_barrier
	s_setprio 0
	ds_read_b128 v[138:141], v160
	ds_read_b128 v[146:149], v160 offset:1024
	ds_read_b128 v[150:153], v160 offset:2048
	ds_read_b128 v[160:163], v160 offset:3072
	s_add_u32 s0, s42, 0x40000
	s_addc_u32 s1, s43, 0
	s_mov_b32 m0, s48
	v_lshl_add_u64 v[208:209], s[0:1], 0, v[132:133]
	ds_read_b128 v[164:167], v145 offset:32768
	ds_read_b128 v[184:187], v145 offset:34816
	ds_read_b128 v[192:195], v145 offset:36864
	ds_read_b128 v[200:203], v145 offset:38912
	global_load_lds_dwordx4 v[208:209], off
	s_waitcnt lgkmcnt(4)
	s_setprio 1
	s_barrier
; #define PG8_STAGE(bufoff, gbase, voff) do { _Pragma("unroll") for (int _i = 0; _i < 2; ++_i) \
;         __builtin_amdgcn_global_load_lds((const unsigned*)((const char*)(gbase) + (voff)[_i]), (LAS unsigned*)(lds + (bufoff) + ldsw + _i * 8192), 16, 0, 0); } while (0)
; #define PG8_LDA(dst, b, h) do { _Pragma("unroll") for (int m = 0; m < 4; ++m) _Pragma("unroll") for (int k = 0; k < 2; ++k) dst[m][k] = *(const LAS bf16x8*)(lds + PG8_SA(b, h) + aoff + m * 2048 + k * 1024); } while (0)
; #define PG8_LDB(dst, b, h) do { _Pragma("unroll") for (int n = 0; n < 2; ++n) _Pragma("unroll") for (int k = 0; k < 2; ++k) dst[n][k] = *(const LAS bf16x8*)(lds + PG8_SB(b, h) + boff + n * 2048 + k * 1024); } while (0)
; #define PG8_MMA(ai, bj, At, Bt) do { __builtin_amdgcn_s_setprio(1); _Pragma("unroll") for (int m = 0; m < 4; ++m) _Pragma("unroll") for (int n = 0; n < 2; ++n) _Pragma("unroll") for (int k = 0; k < 2; ++k) \
;         acc[ai][bj][m][n] = __builtin_amdgcn_mfma_f32_16x16x32_bf16(Bt[n][k], At[m][k], acc[ai][bj][m][n], 0, 0, 0); __builtin_amdgcn_s_setprio(0); } while (0)
; #define PG8_WAIT_V(n) asm volatile("s_waitcnt vmcnt(" #n ")" ::: "memory")
; #define PG8_WAIT_L(n) asm volatile("s_waitcnt lgkmcnt(" #n ")" ::: "memory")
; #define PG8_BAR __builtin_amdgcn_s_barrier()
; #define PG8_SCHED __builtin_amdgcn_sched_barrier(0)
; template <class Epi, class Sched>
; __device__ __forceinline__ void gemm_phase(LAS unsigned char* lds, const Gemm g, const Sched& S, const Epi& E, int tid) {
;     ...
;             PG8_WAIT_L(8); PG8_BAR; PG8_WAIT_L(0); PG8_MMA(0, 0, At, B0); PG8_BAR; PG8_SCHED;
;             PG8_LDB(B1, 1, 1); PG8_STAGE(PG8_SB(1, 0), b3, voffB);
;             PG8_BAR; PG8_WAIT_L(0); PG8_MMA(0, 1, At, B1); PG8_BAR;
;             PG8_LDA(At, 1, 1); PG8_STAGE(PG8_SA(1, 0), a3, voffA);
;             PG8_BAR; PG8_WAIT_L(0); PG8_MMA(1, 0, At, B0); PG8_BAR; PG8_SCHED;
;             PG8_STAGE(PG8_SB(1, 1), b3 + hstep, voffB);
;             PG8_WAIT_V(6); PG8_BAR; PG8_MMA(1, 1, At, B1); PG8_BAR;
	s_waitcnt lgkmcnt(0)
	v_mfma_f32_16x16x32_bf16 v[124:127], v[138:141], v[164:167], v[124:127]
	ds_read_b128 v[168:171], v145 offset:33792
	v_mfma_f32_16x16x32_bf16 v[120:123], v[150:153], v[164:167], v[120:123]
	ds_read_b128 v[188:191], v145 offset:35840
	v_mfma_f32_16x16x32_bf16 v[108:111], v[138:141], v[184:187], v[108:111]
	ds_read_b128 v[196:199], v145 offset:37888
	v_mfma_f32_16x16x32_bf16 v[104:107], v[150:153], v[184:187], v[104:107]
	ds_read_b128 v[204:207], v145 offset:39936
	v_mfma_f32_16x16x32_bf16 v[92:95], v[138:141], v[192:195], v[92:95]
	v_mfma_f32_16x16x32_bf16 v[88:91], v[150:153], v[192:195], v[88:91]
	v_mfma_f32_16x16x32_bf16 v[76:79], v[138:141], v[200:203], v[76:79]
	v_mfma_f32_16x16x32_bf16 v[72:75], v[150:153], v[200:203], v[72:75]
	s_waitcnt lgkmcnt(0)
	v_mfma_f32_16x16x32_bf16 v[124:127], v[146:149], v[168:171], v[124:127]
	s_add_i32 s42, 0, 0x1c000
	v_add_u32_e32 v183, s42, v143
	v_mfma_f32_16x16x32_bf16 v[120:123], v[160:163], v[168:171], v[120:123]
	ds_read_b128 v[208:211], v183
	v_mfma_f32_16x16x32_bf16 v[108:111], v[146:149], v[188:191], v[108:111]
	ds_read_b128 v[212:215], v183 offset:1024
	v_mfma_f32_16x16x32_bf16 v[104:107], v[160:163], v[188:191], v[104:107]
	ds_read_b128 v[216:219], v183 offset:2048
	v_mfma_f32_16x16x32_bf16 v[92:95], v[146:149], v[196:199], v[92:95]
	ds_read_b128 v[220:223], v183 offset:3072
	v_mfma_f32_16x16x32_bf16 v[88:91], v[160:163], v[196:199], v[88:91]
	v_mfma_f32_16x16x32_bf16 v[76:79], v[146:149], v[204:207], v[76:79]
	v_mfma_f32_16x16x32_bf16 v[72:75], v[160:163], v[204:207], v[72:75]
	s_barrier
	s_setprio 0
	v_lshl_add_u64 v[238:239], s[0:1], 0, v[130:131]
	s_mov_b32 m0, s49
	s_nop 0
	global_load_lds_dwordx4 v[238:239], off
	s_add_i32 s0, s17, s45
	v_lshl_add_u64 v[224:225], v[224:225], 0, s[8:9]
	s_mov_b32 m0, s0
	global_load_lds_dwordx4 v[224:225], off
	v_lshl_add_u64 v[224:225], v[226:227], 0, s[8:9]
	s_add_i32 m0, s0, 0x2000
	s_nop 0
	global_load_lds_dwordx4 v[224:225], off
	s_setprio 1
	s_barrier
	s_waitcnt lgkmcnt(0)
	v_mfma_f32_16x16x32_bf16 v[116:119], v[208:211], v[164:167], v[116:119]
	v_mfma_f32_16x16x32_bf16 v[112:115], v[216:219], v[164:167], v[112:115]
	v_mfma_f32_16x16x32_bf16 v[100:103], v[208:211], v[184:187], v[100:103]
	v_mfma_f32_16x16x32_bf16 v[96:99], v[216:219], v[184:187], v[96:99]
	v_mfma_f32_16x16x32_bf16 v[84:87], v[208:211], v[192:195], v[84:87]
	v_mfma_f32_16x16x32_bf16 v[80:83], v[216:219], v[192:195], v[80:83]
	s_mov_b32 m0, s6
	v_mfma_f32_16x16x32_bf16 v[68:71], v[208:211], v[200:203], v[68:71]
	v_lshl_add_u64 v[224:225], v[228:229], 0, s[8:9]
	v_mfma_f32_16x16x32_bf16 v[64:67], v[216:219], v[200:203], v[64:67]
	v_mfma_f32_16x16x32_bf16 v[116:119], v[212:215], v[168:171], v[116:119]
	v_mfma_f32_16x16x32_bf16 v[112:115], v[220:223], v[168:171], v[112:115]
	v_mfma_f32_16x16x32_bf16 v[100:103], v[212:215], v[188:191], v[100:103]
	v_mfma_f32_16x16x32_bf16 v[96:99], v[220:223], v[188:191], v[96:99]
	v_mfma_f32_16x16x32_bf16 v[84:87], v[212:215], v[196:199], v[84:87]
	v_mfma_f32_16x16x32_bf16 v[80:83], v[220:223], v[196:199], v[80:83]
	v_mfma_f32_16x16x32_bf16 v[68:71], v[212:215], v[204:207], v[68:71]
	v_mfma_f32_16x16x32_bf16 v[64:67], v[220:223], v[204:207], v[64:67]
	s_barrier
	s_setprio 0
	ds_read_b128 v[164:167], v145 offset:49152
	ds_read_b128 v[168:171], v145 offset:50176
	ds_read_b128 v[184:187], v145 offset:51200
	ds_read_b128 v[188:191], v145 offset:52224
	ds_read_b128 v[192:195], v145 offset:53248
	ds_read_b128 v[196:199], v145 offset:54272
	ds_read_b128 v[200:203], v145 offset:55296
	ds_read_b128 v[204:207], v145 offset:56320
	global_load_lds_dwordx4 v[224:225], off
	v_lshl_add_u64 v[224:225], v[230:231], 0, s[8:9]
	s_mov_b32 m0, s50
	s_nop 0
	global_load_lds_dwordx4 v[224:225], off
	s_setprio 1
	s_barrier
	s_waitcnt lgkmcnt(0)
	v_mfma_f32_16x16x32_bf16 v[60:63], v[138:141], v[164:167], v[60:63]
	v_mfma_f32_16x16x32_bf16 v[56:59], v[150:153], v[164:167], v[56:59]
	v_mfma_f32_16x16x32_bf16 v[44:47], v[138:141], v[184:187], v[44:47]
	v_mfma_f32_16x16x32_bf16 v[40:43], v[150:153], v[184:187], v[40:43]
	v_mfma_f32_16x16x32_bf16 v[28:31], v[138:141], v[192:195], v[28:31]
	v_mfma_f32_16x16x32_bf16 v[24:27], v[150:153], v[192:195], v[24:27]
	v_mfma_f32_16x16x32_bf16 v[12:15], v[138:141], v[200:203], v[12:15]
	v_mfma_f32_16x16x32_bf16 v[8:11], v[150:153], v[200:203], v[8:11]
	v_mfma_f32_16x16x32_bf16 v[60:63], v[146:149], v[168:171], v[60:63]
	v_mfma_f32_16x16x32_bf16 v[56:59], v[160:163], v[168:171], v[56:59]
	v_mfma_f32_16x16x32_bf16 v[44:47], v[146:149], v[188:191], v[44:47]
	v_mfma_f32_16x16x32_bf16 v[40:43], v[160:163], v[188:191], v[40:43]
	v_mfma_f32_16x16x32_bf16 v[28:31], v[146:149], v[196:199], v[28:31]
	v_mfma_f32_16x16x32_bf16 v[24:27], v[160:163], v[196:199], v[24:27]
	v_mfma_f32_16x16x32_bf16 v[12:15], v[146:149], v[204:207], v[12:15]
	v_mfma_f32_16x16x32_bf16 v[8:11], v[160:163], v[204:207], v[8:11]
	s_barrier
	s_setprio 0
	s_add_u32 s0, s34, 0x40080
	s_addc_u32 s1, s35, 0
	s_add_i32 s17, s42, s45
	v_lshl_add_u64 v[138:139], s[0:1], 0, v[154:155]
	s_mov_b32 m0, s17
	s_nop 0
	global_load_lds_dwordx4 v[138:139], off
	v_lshl_add_u64 v[138:139], s[0:1], 0, v[128:129]
	s_add_i32 m0, s17, 0x2000
	s_nop 0
	global_load_lds_dwordx4 v[138:139], off
	s_waitcnt vmcnt(6)
	s_setprio 1
	s_barrier
	v_mfma_f32_16x16x32_bf16 v[52:55], v[208:211], v[164:167], v[52:55]
	v_mfma_f32_16x16x32_bf16 v[48:51], v[216:219], v[164:167], v[48:51]
	v_mfma_f32_16x16x32_bf16 v[36:39], v[208:211], v[184:187], v[36:39]
	v_mfma_f32_16x16x32_bf16 v[32:35], v[216:219], v[184:187], v[32:35]
	v_mfma_f32_16x16x32_bf16 v[20:23], v[208:211], v[192:195], v[20:23]
	v_mfma_f32_16x16x32_bf16 v[16:19], v[216:219], v[192:195], v[16:19]
	s_add_i32 s61, s61, 2
	v_mfma_f32_16x16x32_bf16 v[4:7], v[208:211], v[200:203], v[4:7]
	s_add_u32 s40, s40, 0x100
	v_mfma_f32_16x16x32_bf16 v[0:3], v[216:219], v[200:203], v[0:3]
	s_addc_u32 s41, s41, 0
	v_mfma_f32_16x16x32_bf16 v[52:55], v[212:215], v[168:171], v[52:55]
	s_add_u32 s58, s58, 0x100
	v_mfma_f32_16x16x32_bf16 v[48:51], v[220:223], v[168:171], v[48:51]
	s_addc_u32 s60, s60, 0
	v_mfma_f32_16x16x32_bf16 v[36:39], v[212:215], v[188:191], v[36:39]
	s_cmp_gt_u32 s61, 13
	v_mfma_f32_16x16x32_bf16 v[32:35], v[220:223], v[188:191], v[32:35]
	v_mfma_f32_16x16x32_bf16 v[20:23], v[212:215], v[196:199], v[20:23]
	v_mfma_f32_16x16x32_bf16 v[16:19], v[220:223], v[196:199], v[16:19]
	v_mfma_f32_16x16x32_bf16 v[4:7], v[212:215], v[204:207], v[4:7]
	v_mfma_f32_16x16x32_bf16 v[0:3], v[220:223], v[204:207], v[0:3]
	s_barrier
	s_setprio 0
	s_cbranch_scc0 .LBB0_115
